# scan waves: the five operand loads of a step are issued back to back right after the y products instead of one per DPP wait slot
# speedup vs baseline: 1.0655x; 1.0261x over previous
; __device__ __forceinline__ void phase_scan(const Params& p, LAS unsigned char* lds) {
;     ...
;                     __builtin_amdgcn_s_setprio(3);
;                     const LAS float* sR = OPS + (n & 1) * SET_F + j0; const LAS float* sW = sR + 2048; const LAS float* sK = sW + 2048; const LAS float* sA = sK + 2048; const LAS float* sB = sA + 2048; const LAS float* sV = OPS + (n & 1) * SET_F + 10240;
;                     LAS float* sY = sYb + (n & 1) * 512;
;                     f32x4 a_ = *(const LAS f32x4*)(sA), w_ = *(const LAS f32x4*)(sW), b_ = *(const LAS f32x4*)(sB);
;                     f32x4 k_ = *(const LAS f32x4*)(sK), r_ = *(const LAS f32x4*)(sR);
;                     f32x4 vq[4];
; #pragma unroll
;                     for (int u = 0; u < 4; ++u) vq[u] = *(const LAS f32x4*)(sV + srow * 32 + 4 * u);
;                     f32x4 rp = r_;
; #pragma unroll
;                     for (int hb = 0; hb < 2; ++hb) {
;                         f32x4 vn[4];
; #pragma unroll
;                         for (int u = 0; u < 4; ++u) vn[u] = *(const LAS f32x4*)(sV + srow * 32 + ((16 * (hb + 1)) & 31) + 4 * u);
; #pragma unroll
;                         for (int u16 = 0; u16 < 16; ++u16) {
;                             const int s = 16 * hb + u16;
;                             const int sn = (s + 1) & 31;
;                             const f32x4 a_n = *(const LAS f32x4*)(sA + sn * 64), w_n = *(const LAS f32x4*)(sW + sn * 64), b_n = *(const LAS f32x4*)(sB + sn * 64);
;                             const f32x4 k_n = *(const LAS f32x4*)(sK + sn * 64), r_n = *(const LAS f32x4*)(sR + sn * 64);
;                             const float v = vq[u16 >> 2][u16 & 3];
;                             const f32x2 vv = {v, v};
;                             f32x2 pp = S01 * (f32x2){a_[0], a_[1]}; pp = S23 * (f32x2){a_[2], a_[3]} + pp;
;                             f32x2 yy = S01 * (f32x2){rp[0], rp[1]}; yy = S23 * (f32x2){rp[2], rp[3]} + yy;
;                             float sa = pp[0] + pp[1], y = yy[0] + yy[1];
;                             sa += dpp_f<0xB1>(sa); y += dpp_f<0xB1>(y);
;                             sa += dpp_f<0x4E>(sa); y += dpp_f<0x4E>(y);
;                             sa += dpp_f<0x141>(sa); y += dpp_f<0x141>(y);
;                             sa += dpp_f<0x140>(sa); y += dpp_f<0x140>(y);
;                             sY[((s - 1) & 31) * 16 + srow] = y;
.Lscan_wave_top:
	s_mov_b64 s[54:55], 0
	s_cmp_lt_i32 s81, 0
	s_cbranch_scc1 .LBB0_603
	s_setprio 3
	s_and_b32 s14, s81, 1
	s_mul_i32 s15, s14, 0xa800
	s_add_i32 s15, s15, 0x8800
	v_add_u32_e32 v124, s15, v178
	v_add_u32_e32 v125, s15, v179
	s_cmp_eq_u32 s81, 0
	s_cselect_b32 s14, 0xc000c000, -1
	s_mov_b32 s15, s14
	v_pk_mul_f32 v[114:115], v[166:167], v[22:23]
	v_pk_mul_f32 v[116:117], v[166:167], v[18:19]
	v_pk_fma_f32 v[114:115], v[164:165], v[24:25], v[114:115]
	v_pk_fma_f32 v[116:117], v[164:165], v[20:21], v[116:117]
	ds_read_b128 v[14:17], v124 offset:16384
	ds_read_b128 v[6:9], v124 offset:8192
	ds_read_b128 v[10:13], v124 offset:32768
	ds_read_b128 v[18:21], v124 offset:0
	ds_read_b128 v[2:5], v124 offset:24576
	ds_read_b128 v[82:85], v125 offset:40960
	v_add_f32_e32 v122, v114, v115
	v_pk_mul_f32 v[118:119], v[110:111], v[34:35] op_sel:[1,0]
	v_add_f32_e32 v214, v116, v117
	v_add_f32_dpp v122, v122, v122 quad_perm:[1,0,3,2] row_mask:0xf bank_mask:0xf bound_ctrl:1
	v_pk_mul_f32 v[120:121], v[110:111], v[36:37] op_sel:[1,0]
	v_add_f32_dpp v204, v204, v204 row_mirror row_mask:0xf bank_mask:0xf bound_ctrl:1
	v_add_f32_dpp v122, v122, v122 quad_perm:[2,3,0,1] row_mask:0xf bank_mask:0xf bound_ctrl:1
	v_pk_fma_f32 v[166:167], v[166:167], v[26:27], v[118:119]
	v_add_f32_dpp v204, v212, v212 row_mirror row_mask:0xf bank_mask:0xc bound_ctrl:1
	v_add_f32_dpp v122, v122, v122 row_half_mirror row_mask:0xf bank_mask:0xf bound_ctrl:1
	v_pk_fma_f32 v[164:165], v[164:165], v[28:29], v[120:121]
	v_add_f32_dpp v205, v205, v205 row_mirror row_mask:0xf bank_mask:0xf bound_ctrl:1
	v_add_f32_dpp v122, v122, v122 row_mirror row_mask:0xf bank_mask:0xf bound_ctrl:1
	v_add_f32_dpp v205, v213, v213 row_mirror row_mask:0xf bank_mask:0xc bound_ctrl:1
	v_add_f32_dpp v206, v206, v206 row_mirror row_mask:0xf bank_mask:0xf bound_ctrl:1
	v_pk_fma_f32 v[166:167], v[30:31], v[122:123], v[166:167] op_sel_hi:[1,0,1]
	v_pk_fma_f32 v[164:165], v[32:33], v[122:123], v[164:165] op_sel_hi:[1,0,1]
	v_add_f32_dpp v206, v214, v214 row_mirror row_mask:0xf bank_mask:0xc bound_ctrl:1
	v_pk_mul_f32 v[114:115], v[166:167], v[42:43]
	v_pk_mul_f32 v[116:117], v[166:167], v[38:39]
	v_pk_fma_f32 v[114:115], v[164:165], v[44:45], v[114:115]
	v_pk_fma_f32 v[116:117], v[164:165], v[40:41], v[116:117]
	ds_read_b128 v[34:37], v124 offset:16640
	ds_read_b128 v[26:29], v124 offset:8448
	ds_read_b128 v[30:33], v124 offset:33024
	ds_read_b128 v[38:41], v124 offset:256
	ds_read_b128 v[22:25], v124 offset:24832
	v_add_f32_e32 v122, v114, v115
	v_pk_mul_f32 v[118:119], v[112:113], v[54:55] op_sel_hi:[0,1]
	v_add_f32_e32 v215, v116, v117
	v_add_f32_dpp v122, v122, v122 quad_perm:[1,0,3,2] row_mask:0xf bank_mask:0xf bound_ctrl:1
	v_pk_mul_f32 v[120:121], v[112:113], v[56:57] op_sel_hi:[0,1]
	v_add_f32_dpp v207, v207, v207 row_mirror row_mask:0xf bank_mask:0xf bound_ctrl:1
	v_add_f32_dpp v122, v122, v122 quad_perm:[2,3,0,1] row_mask:0xf bank_mask:0xf bound_ctrl:1
	v_pk_fma_f32 v[166:167], v[166:167], v[46:47], v[118:119]
	v_add_f32_dpp v207, v215, v215 row_mirror row_mask:0xf bank_mask:0xc bound_ctrl:1
	v_add_f32_dpp v122, v122, v122 row_half_mirror row_mask:0xf bank_mask:0xf bound_ctrl:1
	v_pk_fma_f32 v[164:165], v[164:165], v[48:49], v[120:121]
	s_nop 0
	v_add_f32_dpp v122, v122, v122 row_mirror row_mask:0xf bank_mask:0xf bound_ctrl:1
	s_nop 0
	v_pk_fma_f32 v[166:167], v[50:51], v[122:123], v[166:167] op_sel_hi:[1,0,1]
	v_pk_fma_f32 v[164:165], v[52:53], v[122:123], v[164:165] op_sel_hi:[1,0,1]
	v_pk_mul_f32 v[114:115], v[166:167], v[62:63]
	v_pk_mul_f32 v[116:117], v[166:167], v[58:59]
	v_pk_fma_f32 v[114:115], v[164:165], v[64:65], v[114:115]
	v_pk_fma_f32 v[116:117], v[164:165], v[60:61], v[116:117]
	ds_read_b128 v[54:57], v124 offset:16896
	ds_read_b128 v[46:49], v124 offset:8704
	ds_read_b128 v[50:53], v124 offset:33280
	ds_read_b128 v[58:61], v124 offset:512
	ds_read_b128 v[42:45], v124 offset:25088
	v_add_f32_e32 v122, v114, v115
	v_pk_mul_f32 v[118:119], v[112:113], v[74:75] op_sel:[1,0]
	v_add_f32_e32 v216, v116, v117
	v_add_f32_dpp v122, v122, v122 quad_perm:[1,0,3,2] row_mask:0xf bank_mask:0xf bound_ctrl:1
	v_pk_mul_f32 v[120:121], v[112:113], v[76:77] op_sel:[1,0]
	v_add_f32_dpp v208, v208, v208 row_mirror row_mask:0xf bank_mask:0xf bound_ctrl:1
	v_add_f32_dpp v122, v122, v122 quad_perm:[2,3,0,1] row_mask:0xf bank_mask:0xf bound_ctrl:1
	v_pk_fma_f32 v[166:167], v[166:167], v[66:67], v[118:119]
	v_add_f32_dpp v208, v216, v216 row_mirror row_mask:0xf bank_mask:0xc bound_ctrl:1
	v_add_f32_dpp v122, v122, v122 row_half_mirror row_mask:0xf bank_mask:0xf bound_ctrl:1
	v_pk_fma_f32 v[164:165], v[164:165], v[68:69], v[120:121]
	s_nop 0
	v_add_f32_dpp v122, v122, v122 row_mirror row_mask:0xf bank_mask:0xf bound_ctrl:1
	s_nop 0
	v_pk_fma_f32 v[166:167], v[70:71], v[122:123], v[166:167] op_sel_hi:[1,0,1]
	v_pk_fma_f32 v[164:165], v[72:73], v[122:123], v[164:165] op_sel_hi:[1,0,1]
	s_waitcnt lgkmcnt(11)
	v_pk_mul_f32 v[114:115], v[166:167], v[2:3]
	v_pk_mul_f32 v[116:117], v[166:167], v[78:79]
	v_pk_fma_f32 v[114:115], v[164:165], v[4:5], v[114:115]
	v_pk_fma_f32 v[116:117], v[164:165], v[80:81], v[116:117]
	ds_read_b128 v[74:77], v124 offset:17152
	ds_read_b128 v[66:69], v124 offset:8960
	ds_read_b128 v[70:73], v124 offset:33536
	ds_read_b128 v[78:81], v124 offset:768
	ds_read_b128 v[62:65], v124 offset:25344
	v_add_f32_e32 v122, v114, v115
	s_waitcnt lgkmcnt(15)
; #define LAS __attribute__((address_space(3)))
; template <int CTRL> __device__ __forceinline__ float dpp_f(float x) { return __int_as_float(__builtin_amdgcn_update_dpp(0, __float_as_int(x), CTRL, 0xf, 0xf, false)); }
; __device__ __forceinline__ void phase_scan(const Params& p, LAS unsigned char* lds) {
;     ...
;                         for (int u16 = 0; u16 < 16; ++u16) {
;                             const int s = 16 * hb + u16;
;                             const int sn = (s + 1) & 31;
;                             const f32x4 a_n = *(const LAS f32x4*)(sA + sn * 64), w_n = *(const LAS f32x4*)(sW + sn * 64), b_n = *(const LAS f32x4*)(sB + sn * 64);
;                             const f32x4 k_n = *(const LAS f32x4*)(sK + sn * 64), r_n = *(const LAS f32x4*)(sR + sn * 64);
;                             const float v = vq[u16 >> 2][u16 & 3];
;                             const f32x2 vv = {v, v};
;                             f32x2 pp = S01 * (f32x2){a_[0], a_[1]}; pp = S23 * (f32x2){a_[2], a_[3]} + pp;
;                             f32x2 yy = S01 * (f32x2){rp[0], rp[1]}; yy = S23 * (f32x2){rp[2], rp[3]} + yy;
;                             float sa = pp[0] + pp[1], y = yy[0] + yy[1];
;                             sa += dpp_f<0xB1>(sa); y += dpp_f<0xB1>(y);
;                             sa += dpp_f<0x4E>(sa); y += dpp_f<0x4E>(y);
;                             sa += dpp_f<0x141>(sa); y += dpp_f<0x141>(y);
;                             sa += dpp_f<0x140>(sa); y += dpp_f<0x140>(y);
;                             sY[((s - 1) & 31) * 16 + srow] = y;
;                             const f32x2 sv = {sa, sa};
;                             S01 = S01 * (f32x2){w_[0], w_[1]} + vv * (f32x2){k_[0], k_[1]};
;                             S23 = S23 * (f32x2){w_[2], w_[3]} + vv * (f32x2){k_[2], k_[3]};
;                             S01 = sv * (f32x2){b_[0], b_[1]} + S01;
;                             S23 = sv * (f32x2){b_[2], b_[3]} + S23;
;                             rp = r_;
;                             a_ = a_n; w_ = w_n; b_ = b_n; k_ = k_n; r_ = r_n;
	v_pk_mul_f32 v[118:119], v[82:83], v[14:15] op_sel_hi:[0,1]
	v_add_f32_e32 v217, v116, v117
	v_add_f32_dpp v122, v122, v122 quad_perm:[1,0,3,2] row_mask:0xf bank_mask:0xf bound_ctrl:1
	v_pk_mul_f32 v[120:121], v[82:83], v[16:17] op_sel_hi:[0,1]
	v_add_f32_dpp v209, v209, v209 row_mirror row_mask:0xf bank_mask:0xf bound_ctrl:1
	v_add_f32_dpp v122, v122, v122 quad_perm:[2,3,0,1] row_mask:0xf bank_mask:0xf bound_ctrl:1
	v_pk_fma_f32 v[166:167], v[166:167], v[6:7], v[118:119]
	v_add_f32_dpp v209, v217, v217 row_mirror row_mask:0xf bank_mask:0xc bound_ctrl:1
	v_add_f32_dpp v122, v122, v122 row_half_mirror row_mask:0xf bank_mask:0xf bound_ctrl:1
	v_pk_fma_f32 v[164:165], v[164:165], v[8:9], v[120:121]
	s_nop 0
	v_add_f32_dpp v122, v122, v122 row_mirror row_mask:0xf bank_mask:0xf bound_ctrl:1
	s_nop 0
	v_pk_fma_f32 v[166:167], v[10:11], v[122:123], v[166:167] op_sel_hi:[1,0,1]
	v_pk_fma_f32 v[164:165], v[12:13], v[122:123], v[164:165] op_sel_hi:[1,0,1]
	s_waitcnt lgkmcnt(10)
	v_pk_mul_f32 v[114:115], v[166:167], v[22:23]
	v_pk_mul_f32 v[116:117], v[166:167], v[18:19]
	v_pk_fma_f32 v[114:115], v[164:165], v[24:25], v[114:115]
	v_pk_fma_f32 v[116:117], v[164:165], v[20:21], v[116:117]
	ds_read_b128 v[14:17], v124 offset:17408
	ds_read_b128 v[6:9], v124 offset:9216
	ds_read_b128 v[10:13], v124 offset:33792
	ds_read_b128 v[18:21], v124 offset:1024
	ds_read_b128 v[2:5], v124 offset:25600
	ds_read_b128 v[86:89], v125 offset:40976
	v_add_f32_e32 v122, v114, v115
	v_pk_mul_f32 v[118:119], v[82:83], v[34:35] op_sel:[1,0]
	v_add_f32_e32 v218, v116, v117
	v_add_f32_dpp v122, v122, v122 quad_perm:[1,0,3,2] row_mask:0xf bank_mask:0xf bound_ctrl:1
	v_pk_mul_f32 v[120:121], v[82:83], v[36:37] op_sel:[1,0]
	v_add_f32_dpp v210, v210, v210 row_mirror row_mask:0xf bank_mask:0xf bound_ctrl:1
	v_add_f32_dpp v122, v122, v122 quad_perm:[2,3,0,1] row_mask:0xf bank_mask:0xf bound_ctrl:1
	v_pk_fma_f32 v[166:167], v[166:167], v[26:27], v[118:119]
	v_add_f32_dpp v210, v218, v218 row_mirror row_mask:0xf bank_mask:0xc bound_ctrl:1
	v_add_f32_dpp v122, v122, v122 row_half_mirror row_mask:0xf bank_mask:0xf bound_ctrl:1
	v_pk_fma_f32 v[164:165], v[164:165], v[28:29], v[120:121]
	s_nop 0
	v_add_f32_dpp v122, v122, v122 row_mirror row_mask:0xf bank_mask:0xf bound_ctrl:1
	s_nop 0
	v_pk_fma_f32 v[166:167], v[30:31], v[122:123], v[166:167] op_sel_hi:[1,0,1]
	v_pk_fma_f32 v[164:165], v[32:33], v[122:123], v[164:165] op_sel_hi:[1,0,1]
	s_waitcnt lgkmcnt(11)
	v_pk_mul_f32 v[114:115], v[166:167], v[42:43]
	v_pk_mul_f32 v[116:117], v[166:167], v[38:39]
	v_pk_fma_f32 v[114:115], v[164:165], v[44:45], v[114:115]
	v_pk_fma_f32 v[116:117], v[164:165], v[40:41], v[116:117]
	ds_read_b128 v[34:37], v124 offset:17664
	ds_read_b128 v[26:29], v124 offset:9472
	ds_read_b128 v[30:33], v124 offset:34048
	ds_read_b128 v[38:41], v124 offset:1280
	ds_read_b128 v[22:25], v124 offset:25856
	v_add_f32_e32 v122, v114, v115
	v_pk_mul_f32 v[118:119], v[84:85], v[54:55] op_sel_hi:[0,1]
	v_add_f32_e32 v219, v116, v117
	v_add_f32_dpp v122, v122, v122 quad_perm:[1,0,3,2] row_mask:0xf bank_mask:0xf bound_ctrl:1
	v_pk_mul_f32 v[120:121], v[84:85], v[56:57] op_sel_hi:[0,1]
	v_add_f32_dpp v211, v211, v211 row_mirror row_mask:0xf bank_mask:0xf bound_ctrl:1
	v_add_f32_dpp v122, v122, v122 quad_perm:[2,3,0,1] row_mask:0xf bank_mask:0xf bound_ctrl:1
	v_pk_fma_f32 v[166:167], v[166:167], v[46:47], v[118:119]
	v_add_f32_dpp v211, v219, v219 row_mirror row_mask:0xf bank_mask:0xc bound_ctrl:1
	v_add_f32_dpp v122, v122, v122 row_half_mirror row_mask:0xf bank_mask:0xf bound_ctrl:1
	v_pk_fma_f32 v[164:165], v[164:165], v[48:49], v[120:121]
	v_add_f32_dpp v204, v204, v204 row_half_mirror row_mask:0xf bank_mask:0xf bound_ctrl:1
	v_add_f32_dpp v122, v122, v122 row_mirror row_mask:0xf bank_mask:0xf bound_ctrl:1
	v_add_f32_dpp v205, v205, v205 row_half_mirror row_mask:0xf bank_mask:0xf bound_ctrl:1
	v_add_f32_dpp v206, v206, v206 row_half_mirror row_mask:0xf bank_mask:0xf bound_ctrl:1
	v_pk_fma_f32 v[166:167], v[50:51], v[122:123], v[166:167] op_sel_hi:[1,0,1]
	v_pk_fma_f32 v[164:165], v[52:53], v[122:123], v[164:165] op_sel_hi:[1,0,1]
	v_add_f32_dpp v207, v207, v207 row_half_mirror row_mask:0xf bank_mask:0xf bound_ctrl:1
	v_add_f32_dpp v204, v208, v208 row_half_mirror row_mask:0xf bank_mask:0xa bound_ctrl:1
	s_waitcnt lgkmcnt(11)
	v_pk_mul_f32 v[114:115], v[166:167], v[62:63]
	v_pk_mul_f32 v[116:117], v[166:167], v[58:59]
	v_pk_fma_f32 v[114:115], v[164:165], v[64:65], v[114:115]
	v_pk_fma_f32 v[116:117], v[164:165], v[60:61], v[116:117]
	ds_read_b128 v[54:57], v124 offset:17920
	ds_read_b128 v[46:49], v124 offset:9728
	ds_read_b128 v[50:53], v124 offset:34304
	ds_read_b128 v[58:61], v124 offset:1536
	ds_read_b128 v[42:45], v124 offset:26112
	v_add_f32_e32 v122, v114, v115
	v_pk_mul_f32 v[118:119], v[84:85], v[74:75] op_sel:[1,0]
	v_add_f32_e32 v220, v116, v117
	v_add_f32_dpp v122, v122, v122 quad_perm:[1,0,3,2] row_mask:0xf bank_mask:0xf bound_ctrl:1
	v_pk_mul_f32 v[120:121], v[84:85], v[76:77] op_sel:[1,0]
	v_add_f32_dpp v205, v209, v209 row_half_mirror row_mask:0xf bank_mask:0xa bound_ctrl:1
	v_add_f32_dpp v122, v122, v122 quad_perm:[2,3,0,1] row_mask:0xf bank_mask:0xf bound_ctrl:1
	v_pk_fma_f32 v[166:167], v[166:167], v[66:67], v[118:119]
	v_add_f32_dpp v206, v210, v210 row_half_mirror row_mask:0xf bank_mask:0xa bound_ctrl:1
	v_add_f32_dpp v122, v122, v122 row_half_mirror row_mask:0xf bank_mask:0xf bound_ctrl:1
	v_pk_fma_f32 v[164:165], v[164:165], v[68:69], v[120:121]
	v_add_f32_dpp v207, v211, v211 row_half_mirror row_mask:0xf bank_mask:0xa bound_ctrl:1
	v_add_f32_dpp v122, v122, v122 row_mirror row_mask:0xf bank_mask:0xf bound_ctrl:1
	v_add_f32_dpp v204, v204, v204 quad_perm:[1,0,3,2] row_mask:0xf bank_mask:0xf bound_ctrl:1
	v_add_f32_dpp v205, v205, v205 quad_perm:[1,0,3,2] row_mask:0xf bank_mask:0xf bound_ctrl:1
	v_pk_fma_f32 v[166:167], v[70:71], v[122:123], v[166:167] op_sel_hi:[1,0,1]
	v_pk_fma_f32 v[164:165], v[72:73], v[122:123], v[164:165] op_sel_hi:[1,0,1]
	v_add_f32_dpp v206, v206, v206 quad_perm:[1,0,3,2] row_mask:0xf bank_mask:0xf bound_ctrl:1
	v_add_f32_dpp v207, v207, v207 quad_perm:[1,0,3,2] row_mask:0xf bank_mask:0xf bound_ctrl:1
	s_waitcnt lgkmcnt(11)
; #define LAS __attribute__((address_space(3)))
; template <int CTRL> __device__ __forceinline__ float dpp_f(float x) { return __int_as_float(__builtin_amdgcn_update_dpp(0, __float_as_int(x), CTRL, 0xf, 0xf, false)); }
; __device__ __forceinline__ void phase_scan(const Params& p, LAS unsigned char* lds) {
;     ...
;                         for (int u16 = 0; u16 < 16; ++u16) {
;                             const int s = 16 * hb + u16;
;                             const int sn = (s + 1) & 31;
;                             const f32x4 a_n = *(const LAS f32x4*)(sA + sn * 64), w_n = *(const LAS f32x4*)(sW + sn * 64), b_n = *(const LAS f32x4*)(sB + sn * 64);
;                             const f32x4 k_n = *(const LAS f32x4*)(sK + sn * 64), r_n = *(const LAS f32x4*)(sR + sn * 64);
;                             const float v = vq[u16 >> 2][u16 & 3];
;                             const f32x2 vv = {v, v};
;                             f32x2 pp = S01 * (f32x2){a_[0], a_[1]}; pp = S23 * (f32x2){a_[2], a_[3]} + pp;
;                             f32x2 yy = S01 * (f32x2){rp[0], rp[1]}; yy = S23 * (f32x2){rp[2], rp[3]} + yy;
;                             float sa = pp[0] + pp[1], y = yy[0] + yy[1];
;                             sa += dpp_f<0xB1>(sa); y += dpp_f<0xB1>(y);
;                             sa += dpp_f<0x4E>(sa); y += dpp_f<0x4E>(y);
;                             sa += dpp_f<0x141>(sa); y += dpp_f<0x141>(y);
;                             sa += dpp_f<0x140>(sa); y += dpp_f<0x140>(y);
;                             sY[((s - 1) & 31) * 16 + srow] = y;
;                             const f32x2 sv = {sa, sa};
;                             S01 = S01 * (f32x2){w_[0], w_[1]} + vv * (f32x2){k_[0], k_[1]};
;                             S23 = S23 * (f32x2){w_[2], w_[3]} + vv * (f32x2){k_[2], k_[3]};
;                             S01 = sv * (f32x2){b_[0], b_[1]} + S01;
;                             S23 = sv * (f32x2){b_[2], b_[3]} + S23;
;                             rp = r_;
;                             a_ = a_n; w_ = w_n; b_ = b_n; k_ = k_n; r_ = r_n;
	v_pk_mul_f32 v[114:115], v[166:167], v[2:3]
	v_pk_mul_f32 v[116:117], v[166:167], v[78:79]
	v_pk_fma_f32 v[114:115], v[164:165], v[4:5], v[114:115]
	v_pk_fma_f32 v[116:117], v[164:165], v[80:81], v[116:117]
	ds_read_b128 v[74:77], v124 offset:18176
	ds_read_b128 v[66:69], v124 offset:9984
	ds_read_b128 v[70:73], v124 offset:34560
	ds_read_b128 v[78:81], v124 offset:1792
	ds_read_b128 v[62:65], v124 offset:26368
	v_add_f32_e32 v122, v114, v115
	s_waitcnt lgkmcnt(15)
	v_pk_mul_f32 v[118:119], v[86:87], v[14:15] op_sel_hi:[0,1]
	v_add_f32_e32 v221, v116, v117
	v_add_f32_dpp v122, v122, v122 quad_perm:[1,0,3,2] row_mask:0xf bank_mask:0xf bound_ctrl:1
	v_pk_mul_f32 v[120:121], v[86:87], v[16:17] op_sel_hi:[0,1]
	v_add_f32_dpp v204, v204, v204 quad_perm:[2,3,0,1] row_mask:0xf bank_mask:0xf bound_ctrl:1
	v_add_f32_dpp v122, v122, v122 quad_perm:[2,3,0,1] row_mask:0xf bank_mask:0xf bound_ctrl:1
	v_pk_fma_f32 v[166:167], v[166:167], v[6:7], v[118:119]
	v_add_f32_dpp v205, v205, v205 quad_perm:[2,3,0,1] row_mask:0xf bank_mask:0xf bound_ctrl:1
	v_add_f32_dpp v122, v122, v122 row_half_mirror row_mask:0xf bank_mask:0xf bound_ctrl:1
	v_pk_fma_f32 v[164:165], v[164:165], v[8:9], v[120:121]
	v_add_f32_dpp v206, v206, v206 quad_perm:[2,3,0,1] row_mask:0xf bank_mask:0xf bound_ctrl:1
	v_add_f32_dpp v122, v122, v122 row_mirror row_mask:0xf bank_mask:0xf bound_ctrl:1
	v_add_f32_dpp v207, v207, v207 quad_perm:[2,3,0,1] row_mask:0xf bank_mask:0xf bound_ctrl:1
	v_cndmask_b32_e64 v202, v204, v205, s[34:35]
	v_pk_fma_f32 v[166:167], v[10:11], v[122:123], v[166:167] op_sel_hi:[1,0,1]
	v_pk_fma_f32 v[164:165], v[12:13], v[122:123], v[164:165] op_sel_hi:[1,0,1]
	v_cndmask_b32_e64 v202, v202, v206, s[56:57]
	v_cndmask_b32_e64 v202, v202, v207, s[98:99]
	s_waitcnt lgkmcnt(10)
	v_pk_mul_f32 v[114:115], v[166:167], v[22:23]
	v_pk_mul_f32 v[116:117], v[166:167], v[18:19]
	v_pk_fma_f32 v[114:115], v[164:165], v[24:25], v[114:115]
	v_pk_fma_f32 v[116:117], v[164:165], v[20:21], v[116:117]
	ds_read_b128 v[14:17], v124 offset:18432
	ds_read_b128 v[6:9], v124 offset:10240
	ds_read_b128 v[10:13], v124 offset:34816
	ds_read_b128 v[18:21], v124 offset:2048
	ds_read_b128 v[2:5], v124 offset:26624
	ds_read_b128 v[90:93], v125 offset:40992
	v_add_f32_e32 v122, v114, v115
	v_pk_mul_f32 v[118:119], v[86:87], v[34:35] op_sel:[1,0]
	v_add_f32_e32 v222, v116, v117
	v_add_f32_dpp v122, v122, v122 quad_perm:[1,0,3,2] row_mask:0xf bank_mask:0xf bound_ctrl:1
	v_pk_mul_f32 v[120:121], v[86:87], v[36:37] op_sel:[1,0]
	v_cvt_f16_f32_e32 v203, v202
	v_add_f32_dpp v122, v122, v122 quad_perm:[2,3,0,1] row_mask:0xf bank_mask:0xf bound_ctrl:1
	v_pk_fma_f32 v[166:167], v[166:167], v[26:27], v[118:119]
	s_mov_b64 exec, s[14:15]
	global_store_short v[128:129], v203, off
	s_mov_b64 exec, -1
	v_add_f32_dpp v122, v122, v122 row_half_mirror row_mask:0xf bank_mask:0xf bound_ctrl:1
	v_pk_fma_f32 v[164:165], v[164:165], v[28:29], v[120:121]
	v_lshl_add_u64 v[128:129], v[128:129], 0, s[100:101]
	v_add_f32_dpp v122, v122, v122 row_mirror row_mask:0xf bank_mask:0xf bound_ctrl:1
	s_nop 0
	v_pk_fma_f32 v[166:167], v[30:31], v[122:123], v[166:167] op_sel_hi:[1,0,1]
	v_pk_fma_f32 v[164:165], v[32:33], v[122:123], v[164:165] op_sel_hi:[1,0,1]
	s_waitcnt lgkmcnt(11)
	v_pk_mul_f32 v[114:115], v[166:167], v[42:43]
	v_pk_mul_f32 v[116:117], v[166:167], v[38:39]
	v_pk_fma_f32 v[114:115], v[164:165], v[44:45], v[114:115]
	v_pk_fma_f32 v[116:117], v[164:165], v[40:41], v[116:117]
	ds_read_b128 v[34:37], v124 offset:18688
	ds_read_b128 v[26:29], v124 offset:10496
	ds_read_b128 v[30:33], v124 offset:35072
	ds_read_b128 v[38:41], v124 offset:2304
	ds_read_b128 v[22:25], v124 offset:26880
	v_add_f32_e32 v122, v114, v115
	v_pk_mul_f32 v[118:119], v[88:89], v[54:55] op_sel_hi:[0,1]
	v_add_f32_e32 v223, v116, v117
	v_add_f32_dpp v122, v122, v122 quad_perm:[1,0,3,2] row_mask:0xf bank_mask:0xf bound_ctrl:1
	v_pk_mul_f32 v[120:121], v[88:89], v[56:57] op_sel_hi:[0,1]
	s_nop 0
	v_add_f32_dpp v122, v122, v122 quad_perm:[2,3,0,1] row_mask:0xf bank_mask:0xf bound_ctrl:1
	v_pk_fma_f32 v[166:167], v[166:167], v[46:47], v[118:119]
	s_nop 0
	v_add_f32_dpp v122, v122, v122 row_half_mirror row_mask:0xf bank_mask:0xf bound_ctrl:1
	v_pk_fma_f32 v[164:165], v[164:165], v[48:49], v[120:121]
	s_nop 0
	v_add_f32_dpp v122, v122, v122 row_mirror row_mask:0xf bank_mask:0xf bound_ctrl:1
	s_nop 0
	v_pk_fma_f32 v[166:167], v[50:51], v[122:123], v[166:167] op_sel_hi:[1,0,1]
	v_pk_fma_f32 v[164:165], v[52:53], v[122:123], v[164:165] op_sel_hi:[1,0,1]
	s_waitcnt lgkmcnt(11)
	v_pk_mul_f32 v[114:115], v[166:167], v[62:63]
	v_pk_mul_f32 v[116:117], v[166:167], v[58:59]
	v_pk_fma_f32 v[114:115], v[164:165], v[64:65], v[114:115]
	v_pk_fma_f32 v[116:117], v[164:165], v[60:61], v[116:117]
	ds_read_b128 v[54:57], v124 offset:18944
	ds_read_b128 v[46:49], v124 offset:10752
	ds_read_b128 v[50:53], v124 offset:35328
	ds_read_b128 v[58:61], v124 offset:2560
	ds_read_b128 v[42:45], v124 offset:27136
	v_add_f32_e32 v122, v114, v115
	v_pk_mul_f32 v[118:119], v[88:89], v[74:75] op_sel:[1,0]
	v_add_f32_e32 v224, v116, v117
	v_add_f32_dpp v122, v122, v122 quad_perm:[1,0,3,2] row_mask:0xf bank_mask:0xf bound_ctrl:1
	v_pk_mul_f32 v[120:121], v[88:89], v[76:77] op_sel:[1,0]
	s_nop 0
	v_add_f32_dpp v122, v122, v122 quad_perm:[2,3,0,1] row_mask:0xf bank_mask:0xf bound_ctrl:1
	v_pk_fma_f32 v[166:167], v[166:167], v[66:67], v[118:119]
	s_nop 0
	v_add_f32_dpp v122, v122, v122 row_half_mirror row_mask:0xf bank_mask:0xf bound_ctrl:1
	v_pk_fma_f32 v[164:165], v[164:165], v[68:69], v[120:121]
	s_nop 0
	v_add_f32_dpp v122, v122, v122 row_mirror row_mask:0xf bank_mask:0xf bound_ctrl:1
	s_nop 0
	v_pk_fma_f32 v[166:167], v[70:71], v[122:123], v[166:167] op_sel_hi:[1,0,1]
	v_pk_fma_f32 v[164:165], v[72:73], v[122:123], v[164:165] op_sel_hi:[1,0,1]
	s_waitcnt lgkmcnt(11)
; #define LAS __attribute__((address_space(3)))
; template <int CTRL> __device__ __forceinline__ float dpp_f(float x) { return __int_as_float(__builtin_amdgcn_update_dpp(0, __float_as_int(x), CTRL, 0xf, 0xf, false)); }
; __device__ __forceinline__ void phase_scan(const Params& p, LAS unsigned char* lds) {
;     ...
;                         for (int u16 = 0; u16 < 16; ++u16) {
;                             const int s = 16 * hb + u16;
;                             const int sn = (s + 1) & 31;
;                             const f32x4 a_n = *(const LAS f32x4*)(sA + sn * 64), w_n = *(const LAS f32x4*)(sW + sn * 64), b_n = *(const LAS f32x4*)(sB + sn * 64);
;                             const f32x4 k_n = *(const LAS f32x4*)(sK + sn * 64), r_n = *(const LAS f32x4*)(sR + sn * 64);
;                             const float v = vq[u16 >> 2][u16 & 3];
;                             const f32x2 vv = {v, v};
;                             f32x2 pp = S01 * (f32x2){a_[0], a_[1]}; pp = S23 * (f32x2){a_[2], a_[3]} + pp;
;                             f32x2 yy = S01 * (f32x2){rp[0], rp[1]}; yy = S23 * (f32x2){rp[2], rp[3]} + yy;
;                             float sa = pp[0] + pp[1], y = yy[0] + yy[1];
;                             sa += dpp_f<0xB1>(sa); y += dpp_f<0xB1>(y);
;                             sa += dpp_f<0x4E>(sa); y += dpp_f<0x4E>(y);
;                             sa += dpp_f<0x141>(sa); y += dpp_f<0x141>(y);
;                             sa += dpp_f<0x140>(sa); y += dpp_f<0x140>(y);
;                             sY[((s - 1) & 31) * 16 + srow] = y;
;                             const f32x2 sv = {sa, sa};
;                             S01 = S01 * (f32x2){w_[0], w_[1]} + vv * (f32x2){k_[0], k_[1]};
;                             S23 = S23 * (f32x2){w_[2], w_[3]} + vv * (f32x2){k_[2], k_[3]};
;                             S01 = sv * (f32x2){b_[0], b_[1]} + S01;
;                             S23 = sv * (f32x2){b_[2], b_[3]} + S23;
;                             rp = r_;
;                             a_ = a_n; w_ = w_n; b_ = b_n; k_ = k_n; r_ = r_n;
	v_pk_mul_f32 v[114:115], v[166:167], v[2:3]
	v_pk_mul_f32 v[116:117], v[166:167], v[78:79]
	v_pk_fma_f32 v[114:115], v[164:165], v[4:5], v[114:115]
	v_pk_fma_f32 v[116:117], v[164:165], v[80:81], v[116:117]
	ds_read_b128 v[74:77], v124 offset:19200
	ds_read_b128 v[66:69], v124 offset:11008
	ds_read_b128 v[70:73], v124 offset:35584
	ds_read_b128 v[78:81], v124 offset:2816
	ds_read_b128 v[62:65], v124 offset:27392
	v_add_f32_e32 v122, v114, v115
	s_waitcnt lgkmcnt(15)
	v_pk_mul_f32 v[118:119], v[90:91], v[14:15] op_sel_hi:[0,1]
	v_add_f32_e32 v225, v116, v117
	v_add_f32_dpp v122, v122, v122 quad_perm:[1,0,3,2] row_mask:0xf bank_mask:0xf bound_ctrl:1
	v_pk_mul_f32 v[120:121], v[90:91], v[16:17] op_sel_hi:[0,1]
	s_nop 0
	v_add_f32_dpp v122, v122, v122 quad_perm:[2,3,0,1] row_mask:0xf bank_mask:0xf bound_ctrl:1
	v_pk_fma_f32 v[166:167], v[166:167], v[6:7], v[118:119]
	s_nop 0
	v_add_f32_dpp v122, v122, v122 row_half_mirror row_mask:0xf bank_mask:0xf bound_ctrl:1
	v_pk_fma_f32 v[164:165], v[164:165], v[8:9], v[120:121]
	s_nop 0
	v_add_f32_dpp v122, v122, v122 row_mirror row_mask:0xf bank_mask:0xf bound_ctrl:1
	s_nop 0
	v_pk_fma_f32 v[166:167], v[10:11], v[122:123], v[166:167] op_sel_hi:[1,0,1]
	v_pk_fma_f32 v[164:165], v[12:13], v[122:123], v[164:165] op_sel_hi:[1,0,1]
	s_waitcnt lgkmcnt(10)
	v_pk_mul_f32 v[114:115], v[166:167], v[22:23]
	v_pk_mul_f32 v[116:117], v[166:167], v[18:19]
	v_pk_fma_f32 v[114:115], v[164:165], v[24:25], v[114:115]
	v_pk_fma_f32 v[116:117], v[164:165], v[20:21], v[116:117]
	ds_read_b128 v[14:17], v124 offset:19456
	ds_read_b128 v[6:9], v124 offset:11264
	ds_read_b128 v[10:13], v124 offset:35840
	ds_read_b128 v[18:21], v124 offset:3072
	ds_read_b128 v[2:5], v124 offset:27648
	ds_read_b128 v[94:97], v125 offset:41008
	v_add_f32_e32 v122, v114, v115
	v_pk_mul_f32 v[118:119], v[90:91], v[34:35] op_sel:[1,0]
	v_add_f32_e32 v226, v116, v117
	v_add_f32_dpp v122, v122, v122 quad_perm:[1,0,3,2] row_mask:0xf bank_mask:0xf bound_ctrl:1
	v_pk_mul_f32 v[120:121], v[90:91], v[36:37] op_sel:[1,0]
	s_nop 0
	v_add_f32_dpp v122, v122, v122 quad_perm:[2,3,0,1] row_mask:0xf bank_mask:0xf bound_ctrl:1
	v_pk_fma_f32 v[166:167], v[166:167], v[26:27], v[118:119]
	s_nop 0
	v_add_f32_dpp v122, v122, v122 row_half_mirror row_mask:0xf bank_mask:0xf bound_ctrl:1
	v_pk_fma_f32 v[164:165], v[164:165], v[28:29], v[120:121]
	s_nop 0
	v_add_f32_dpp v122, v122, v122 row_mirror row_mask:0xf bank_mask:0xf bound_ctrl:1
	s_nop 0
	v_pk_fma_f32 v[166:167], v[30:31], v[122:123], v[166:167] op_sel_hi:[1,0,1]
	v_pk_fma_f32 v[164:165], v[32:33], v[122:123], v[164:165] op_sel_hi:[1,0,1]
	s_waitcnt lgkmcnt(11)
	v_pk_mul_f32 v[114:115], v[166:167], v[42:43]
	v_pk_mul_f32 v[116:117], v[166:167], v[38:39]
	v_pk_fma_f32 v[114:115], v[164:165], v[44:45], v[114:115]
	v_pk_fma_f32 v[116:117], v[164:165], v[40:41], v[116:117]
	ds_read_b128 v[34:37], v124 offset:19712
	ds_read_b128 v[26:29], v124 offset:11520
	ds_read_b128 v[30:33], v124 offset:36096
	ds_read_b128 v[38:41], v124 offset:3328
	ds_read_b128 v[22:25], v124 offset:27904
	v_add_f32_e32 v122, v114, v115
	v_pk_mul_f32 v[118:119], v[92:93], v[54:55] op_sel_hi:[0,1]
	v_add_f32_e32 v227, v116, v117
	v_add_f32_dpp v122, v122, v122 quad_perm:[1,0,3,2] row_mask:0xf bank_mask:0xf bound_ctrl:1
	v_pk_mul_f32 v[120:121], v[92:93], v[56:57] op_sel_hi:[0,1]
	s_nop 0
	v_add_f32_dpp v122, v122, v122 quad_perm:[2,3,0,1] row_mask:0xf bank_mask:0xf bound_ctrl:1
	v_pk_fma_f32 v[166:167], v[166:167], v[46:47], v[118:119]
	s_nop 0
	v_add_f32_dpp v122, v122, v122 row_half_mirror row_mask:0xf bank_mask:0xf bound_ctrl:1
	v_pk_fma_f32 v[164:165], v[164:165], v[48:49], v[120:121]
	s_nop 0
	v_add_f32_dpp v122, v122, v122 row_mirror row_mask:0xf bank_mask:0xf bound_ctrl:1
	s_nop 0
	v_pk_fma_f32 v[166:167], v[50:51], v[122:123], v[166:167] op_sel_hi:[1,0,1]
	v_pk_fma_f32 v[164:165], v[52:53], v[122:123], v[164:165] op_sel_hi:[1,0,1]
	s_waitcnt lgkmcnt(11)
	v_pk_mul_f32 v[114:115], v[166:167], v[62:63]
	v_pk_mul_f32 v[116:117], v[166:167], v[58:59]
	v_pk_fma_f32 v[114:115], v[164:165], v[64:65], v[114:115]
	v_pk_fma_f32 v[116:117], v[164:165], v[60:61], v[116:117]
	ds_read_b128 v[54:57], v124 offset:19968
	ds_read_b128 v[46:49], v124 offset:11776
	ds_read_b128 v[50:53], v124 offset:36352
	ds_read_b128 v[58:61], v124 offset:3584
	ds_read_b128 v[42:45], v124 offset:28160
	v_add_f32_e32 v122, v114, v115
	v_pk_mul_f32 v[118:119], v[92:93], v[74:75] op_sel:[1,0]
	v_add_f32_e32 v228, v116, v117
	v_add_f32_dpp v122, v122, v122 quad_perm:[1,0,3,2] row_mask:0xf bank_mask:0xf bound_ctrl:1
	v_pk_mul_f32 v[120:121], v[92:93], v[76:77] op_sel:[1,0]
	v_add_f32_dpp v220, v220, v220 row_mirror row_mask:0xf bank_mask:0xf bound_ctrl:1
	v_add_f32_dpp v122, v122, v122 quad_perm:[2,3,0,1] row_mask:0xf bank_mask:0xf bound_ctrl:1
	v_pk_fma_f32 v[166:167], v[166:167], v[66:67], v[118:119]
	v_add_f32_dpp v220, v228, v228 row_mirror row_mask:0xf bank_mask:0xc bound_ctrl:1
	v_add_f32_dpp v122, v122, v122 row_half_mirror row_mask:0xf bank_mask:0xf bound_ctrl:1
	v_pk_fma_f32 v[164:165], v[164:165], v[68:69], v[120:121]
	s_nop 0
	v_add_f32_dpp v122, v122, v122 row_mirror row_mask:0xf bank_mask:0xf bound_ctrl:1
	s_nop 0
	v_pk_fma_f32 v[166:167], v[70:71], v[122:123], v[166:167] op_sel_hi:[1,0,1]
	v_pk_fma_f32 v[164:165], v[72:73], v[122:123], v[164:165] op_sel_hi:[1,0,1]
	s_waitcnt lgkmcnt(11)
	v_pk_mul_f32 v[114:115], v[166:167], v[2:3]
	v_pk_mul_f32 v[116:117], v[166:167], v[78:79]
	v_pk_fma_f32 v[114:115], v[164:165], v[4:5], v[114:115]
	v_pk_fma_f32 v[116:117], v[164:165], v[80:81], v[116:117]
	ds_read_b128 v[74:77], v124 offset:20224
	ds_read_b128 v[66:69], v124 offset:12032
	ds_read_b128 v[70:73], v124 offset:36608
	ds_read_b128 v[78:81], v124 offset:3840
	ds_read_b128 v[62:65], v124 offset:28416
	v_add_f32_e32 v122, v114, v115
	s_waitcnt lgkmcnt(15)
; #define LAS __attribute__((address_space(3)))
; template <int CTRL> __device__ __forceinline__ float dpp_f(float x) { return __int_as_float(__builtin_amdgcn_update_dpp(0, __float_as_int(x), CTRL, 0xf, 0xf, false)); }
; __device__ __forceinline__ void phase_scan(const Params& p, LAS unsigned char* lds) {
;     ...
;                         for (int u16 = 0; u16 < 16; ++u16) {
;                             const int s = 16 * hb + u16;
;                             const int sn = (s + 1) & 31;
;                             const f32x4 a_n = *(const LAS f32x4*)(sA + sn * 64), w_n = *(const LAS f32x4*)(sW + sn * 64), b_n = *(const LAS f32x4*)(sB + sn * 64);
;                             const f32x4 k_n = *(const LAS f32x4*)(sK + sn * 64), r_n = *(const LAS f32x4*)(sR + sn * 64);
;                             const float v = vq[u16 >> 2][u16 & 3];
;                             const f32x2 vv = {v, v};
;                             f32x2 pp = S01 * (f32x2){a_[0], a_[1]}; pp = S23 * (f32x2){a_[2], a_[3]} + pp;
;                             f32x2 yy = S01 * (f32x2){rp[0], rp[1]}; yy = S23 * (f32x2){rp[2], rp[3]} + yy;
;                             float sa = pp[0] + pp[1], y = yy[0] + yy[1];
;                             sa += dpp_f<0xB1>(sa); y += dpp_f<0xB1>(y);
;                             sa += dpp_f<0x4E>(sa); y += dpp_f<0x4E>(y);
;                             sa += dpp_f<0x141>(sa); y += dpp_f<0x141>(y);
;                             sa += dpp_f<0x140>(sa); y += dpp_f<0x140>(y);
;                             sY[((s - 1) & 31) * 16 + srow] = y;
;                             const f32x2 sv = {sa, sa};
;                             S01 = S01 * (f32x2){w_[0], w_[1]} + vv * (f32x2){k_[0], k_[1]};
;                             S23 = S23 * (f32x2){w_[2], w_[3]} + vv * (f32x2){k_[2], k_[3]};
;                             S01 = sv * (f32x2){b_[0], b_[1]} + S01;
;                             S23 = sv * (f32x2){b_[2], b_[3]} + S23;
;                             rp = r_;
;                             a_ = a_n; w_ = w_n; b_ = b_n; k_ = k_n; r_ = r_n;
	v_pk_mul_f32 v[118:119], v[94:95], v[14:15] op_sel_hi:[0,1]
	v_add_f32_e32 v229, v116, v117
	v_add_f32_dpp v122, v122, v122 quad_perm:[1,0,3,2] row_mask:0xf bank_mask:0xf bound_ctrl:1
	v_pk_mul_f32 v[120:121], v[94:95], v[16:17] op_sel_hi:[0,1]
	v_add_f32_dpp v221, v221, v221 row_mirror row_mask:0xf bank_mask:0xf bound_ctrl:1
	v_add_f32_dpp v122, v122, v122 quad_perm:[2,3,0,1] row_mask:0xf bank_mask:0xf bound_ctrl:1
	v_pk_fma_f32 v[166:167], v[166:167], v[6:7], v[118:119]
	v_add_f32_dpp v221, v229, v229 row_mirror row_mask:0xf bank_mask:0xc bound_ctrl:1
	v_add_f32_dpp v122, v122, v122 row_half_mirror row_mask:0xf bank_mask:0xf bound_ctrl:1
	v_pk_fma_f32 v[164:165], v[164:165], v[8:9], v[120:121]
	s_nop 0
	v_add_f32_dpp v122, v122, v122 row_mirror row_mask:0xf bank_mask:0xf bound_ctrl:1
	s_nop 0
	v_pk_fma_f32 v[166:167], v[10:11], v[122:123], v[166:167] op_sel_hi:[1,0,1]
	v_pk_fma_f32 v[164:165], v[12:13], v[122:123], v[164:165] op_sel_hi:[1,0,1]
	s_waitcnt lgkmcnt(10)
	v_pk_mul_f32 v[114:115], v[166:167], v[22:23]
	v_pk_mul_f32 v[116:117], v[166:167], v[18:19]
	v_pk_fma_f32 v[114:115], v[164:165], v[24:25], v[114:115]
	v_pk_fma_f32 v[116:117], v[164:165], v[20:21], v[116:117]
	ds_read_b128 v[14:17], v124 offset:20480
	ds_read_b128 v[6:9], v124 offset:12288
	ds_read_b128 v[10:13], v124 offset:36864
	ds_read_b128 v[18:21], v124 offset:4096
	ds_read_b128 v[2:5], v124 offset:28672
	ds_read_b128 v[98:101], v125 offset:41024
	v_add_f32_e32 v122, v114, v115
	v_pk_mul_f32 v[118:119], v[94:95], v[34:35] op_sel:[1,0]
	v_add_f32_e32 v230, v116, v117
	v_add_f32_dpp v122, v122, v122 quad_perm:[1,0,3,2] row_mask:0xf bank_mask:0xf bound_ctrl:1
	v_pk_mul_f32 v[120:121], v[94:95], v[36:37] op_sel:[1,0]
	v_add_f32_dpp v222, v222, v222 row_mirror row_mask:0xf bank_mask:0xf bound_ctrl:1
	v_add_f32_dpp v122, v122, v122 quad_perm:[2,3,0,1] row_mask:0xf bank_mask:0xf bound_ctrl:1
	v_pk_fma_f32 v[166:167], v[166:167], v[26:27], v[118:119]
	v_add_f32_dpp v222, v230, v230 row_mirror row_mask:0xf bank_mask:0xc bound_ctrl:1
	v_add_f32_dpp v122, v122, v122 row_half_mirror row_mask:0xf bank_mask:0xf bound_ctrl:1
	v_pk_fma_f32 v[164:165], v[164:165], v[28:29], v[120:121]
	s_nop 0
	v_add_f32_dpp v122, v122, v122 row_mirror row_mask:0xf bank_mask:0xf bound_ctrl:1
	s_nop 0
	v_pk_fma_f32 v[166:167], v[30:31], v[122:123], v[166:167] op_sel_hi:[1,0,1]
	v_pk_fma_f32 v[164:165], v[32:33], v[122:123], v[164:165] op_sel_hi:[1,0,1]
	s_waitcnt lgkmcnt(11)
	v_pk_mul_f32 v[114:115], v[166:167], v[42:43]
	v_pk_mul_f32 v[116:117], v[166:167], v[38:39]
	v_pk_fma_f32 v[114:115], v[164:165], v[44:45], v[114:115]
	v_pk_fma_f32 v[116:117], v[164:165], v[40:41], v[116:117]
	ds_read_b128 v[34:37], v124 offset:20736
	ds_read_b128 v[26:29], v124 offset:12544
	ds_read_b128 v[30:33], v124 offset:37120
	ds_read_b128 v[38:41], v124 offset:4352
	ds_read_b128 v[22:25], v124 offset:28928
	v_add_f32_e32 v122, v114, v115
	v_pk_mul_f32 v[118:119], v[96:97], v[54:55] op_sel_hi:[0,1]
	v_add_f32_e32 v231, v116, v117
	v_add_f32_dpp v122, v122, v122 quad_perm:[1,0,3,2] row_mask:0xf bank_mask:0xf bound_ctrl:1
	v_pk_mul_f32 v[120:121], v[96:97], v[56:57] op_sel_hi:[0,1]
	v_add_f32_dpp v223, v223, v223 row_mirror row_mask:0xf bank_mask:0xf bound_ctrl:1
	v_add_f32_dpp v122, v122, v122 quad_perm:[2,3,0,1] row_mask:0xf bank_mask:0xf bound_ctrl:1
	v_pk_fma_f32 v[166:167], v[166:167], v[46:47], v[118:119]
	v_add_f32_dpp v223, v231, v231 row_mirror row_mask:0xf bank_mask:0xc bound_ctrl:1
	v_add_f32_dpp v122, v122, v122 row_half_mirror row_mask:0xf bank_mask:0xf bound_ctrl:1
	v_pk_fma_f32 v[164:165], v[164:165], v[48:49], v[120:121]
	s_nop 0
	v_add_f32_dpp v122, v122, v122 row_mirror row_mask:0xf bank_mask:0xf bound_ctrl:1
	s_nop 0
	v_pk_fma_f32 v[166:167], v[50:51], v[122:123], v[166:167] op_sel_hi:[1,0,1]
	v_pk_fma_f32 v[164:165], v[52:53], v[122:123], v[164:165] op_sel_hi:[1,0,1]
	s_waitcnt lgkmcnt(11)
	v_pk_mul_f32 v[114:115], v[166:167], v[62:63]
	v_pk_mul_f32 v[116:117], v[166:167], v[58:59]
	v_pk_fma_f32 v[114:115], v[164:165], v[64:65], v[114:115]
	v_pk_fma_f32 v[116:117], v[164:165], v[60:61], v[116:117]
	ds_read_b128 v[54:57], v124 offset:20992
	ds_read_b128 v[46:49], v124 offset:12800
	ds_read_b128 v[50:53], v124 offset:37376
	ds_read_b128 v[58:61], v124 offset:4608
	ds_read_b128 v[42:45], v124 offset:29184
	v_add_f32_e32 v122, v114, v115
	v_pk_mul_f32 v[118:119], v[96:97], v[74:75] op_sel:[1,0]
	v_add_f32_e32 v232, v116, v117
	v_add_f32_dpp v122, v122, v122 quad_perm:[1,0,3,2] row_mask:0xf bank_mask:0xf bound_ctrl:1
	v_pk_mul_f32 v[120:121], v[96:97], v[76:77] op_sel:[1,0]
	v_add_f32_dpp v224, v224, v224 row_mirror row_mask:0xf bank_mask:0xf bound_ctrl:1
	v_add_f32_dpp v122, v122, v122 quad_perm:[2,3,0,1] row_mask:0xf bank_mask:0xf bound_ctrl:1
	v_pk_fma_f32 v[166:167], v[166:167], v[66:67], v[118:119]
	v_add_f32_dpp v224, v232, v232 row_mirror row_mask:0xf bank_mask:0xc bound_ctrl:1
	v_add_f32_dpp v122, v122, v122 row_half_mirror row_mask:0xf bank_mask:0xf bound_ctrl:1
	v_pk_fma_f32 v[164:165], v[164:165], v[68:69], v[120:121]
	s_nop 0
	v_add_f32_dpp v122, v122, v122 row_mirror row_mask:0xf bank_mask:0xf bound_ctrl:1
	s_nop 0
	v_pk_fma_f32 v[166:167], v[70:71], v[122:123], v[166:167] op_sel_hi:[1,0,1]
	v_pk_fma_f32 v[164:165], v[72:73], v[122:123], v[164:165] op_sel_hi:[1,0,1]
	s_waitcnt lgkmcnt(11)
	v_pk_mul_f32 v[114:115], v[166:167], v[2:3]
	v_pk_mul_f32 v[116:117], v[166:167], v[78:79]
	v_pk_fma_f32 v[114:115], v[164:165], v[4:5], v[114:115]
	v_pk_fma_f32 v[116:117], v[164:165], v[80:81], v[116:117]
	ds_read_b128 v[74:77], v124 offset:21248
	ds_read_b128 v[66:69], v124 offset:13056
	ds_read_b128 v[70:73], v124 offset:37632
	ds_read_b128 v[78:81], v124 offset:4864
	ds_read_b128 v[62:65], v124 offset:29440
	v_add_f32_e32 v122, v114, v115
	s_waitcnt lgkmcnt(15)
; #define LAS __attribute__((address_space(3)))
; template <int CTRL> __device__ __forceinline__ float dpp_f(float x) { return __int_as_float(__builtin_amdgcn_update_dpp(0, __float_as_int(x), CTRL, 0xf, 0xf, false)); }
; __device__ __forceinline__ void phase_scan(const Params& p, LAS unsigned char* lds) {
;     ...
;                         for (int u16 = 0; u16 < 16; ++u16) {
;                             const int s = 16 * hb + u16;
;                             const int sn = (s + 1) & 31;
;                             const f32x4 a_n = *(const LAS f32x4*)(sA + sn * 64), w_n = *(const LAS f32x4*)(sW + sn * 64), b_n = *(const LAS f32x4*)(sB + sn * 64);
;                             const f32x4 k_n = *(const LAS f32x4*)(sK + sn * 64), r_n = *(const LAS f32x4*)(sR + sn * 64);
;                             const float v = vq[u16 >> 2][u16 & 3];
;                             const f32x2 vv = {v, v};
;                             f32x2 pp = S01 * (f32x2){a_[0], a_[1]}; pp = S23 * (f32x2){a_[2], a_[3]} + pp;
;                             f32x2 yy = S01 * (f32x2){rp[0], rp[1]}; yy = S23 * (f32x2){rp[2], rp[3]} + yy;
;                             float sa = pp[0] + pp[1], y = yy[0] + yy[1];
;                             sa += dpp_f<0xB1>(sa); y += dpp_f<0xB1>(y);
;                             sa += dpp_f<0x4E>(sa); y += dpp_f<0x4E>(y);
;                             sa += dpp_f<0x141>(sa); y += dpp_f<0x141>(y);
;                             sa += dpp_f<0x140>(sa); y += dpp_f<0x140>(y);
;                             sY[((s - 1) & 31) * 16 + srow] = y;
;                             const f32x2 sv = {sa, sa};
;                             S01 = S01 * (f32x2){w_[0], w_[1]} + vv * (f32x2){k_[0], k_[1]};
;                             S23 = S23 * (f32x2){w_[2], w_[3]} + vv * (f32x2){k_[2], k_[3]};
;                             S01 = sv * (f32x2){b_[0], b_[1]} + S01;
;                             S23 = sv * (f32x2){b_[2], b_[3]} + S23;
;                             rp = r_;
;                             a_ = a_n; w_ = w_n; b_ = b_n; k_ = k_n; r_ = r_n;
	v_pk_mul_f32 v[118:119], v[98:99], v[14:15] op_sel_hi:[0,1]
	v_add_f32_e32 v233, v116, v117
	v_add_f32_dpp v122, v122, v122 quad_perm:[1,0,3,2] row_mask:0xf bank_mask:0xf bound_ctrl:1
	v_pk_mul_f32 v[120:121], v[98:99], v[16:17] op_sel_hi:[0,1]
	v_add_f32_dpp v225, v225, v225 row_mirror row_mask:0xf bank_mask:0xf bound_ctrl:1
	v_add_f32_dpp v122, v122, v122 quad_perm:[2,3,0,1] row_mask:0xf bank_mask:0xf bound_ctrl:1
	v_pk_fma_f32 v[166:167], v[166:167], v[6:7], v[118:119]
	v_add_f32_dpp v225, v233, v233 row_mirror row_mask:0xf bank_mask:0xc bound_ctrl:1
	v_add_f32_dpp v122, v122, v122 row_half_mirror row_mask:0xf bank_mask:0xf bound_ctrl:1
	v_pk_fma_f32 v[164:165], v[164:165], v[8:9], v[120:121]
	s_nop 0
	v_add_f32_dpp v122, v122, v122 row_mirror row_mask:0xf bank_mask:0xf bound_ctrl:1
	s_nop 0
	v_pk_fma_f32 v[166:167], v[10:11], v[122:123], v[166:167] op_sel_hi:[1,0,1]
	v_pk_fma_f32 v[164:165], v[12:13], v[122:123], v[164:165] op_sel_hi:[1,0,1]
	s_waitcnt lgkmcnt(10)
	v_pk_mul_f32 v[114:115], v[166:167], v[22:23]
	v_pk_mul_f32 v[116:117], v[166:167], v[18:19]
	v_pk_fma_f32 v[114:115], v[164:165], v[24:25], v[114:115]
	v_pk_fma_f32 v[116:117], v[164:165], v[20:21], v[116:117]
	ds_read_b128 v[14:17], v124 offset:21504
	ds_read_b128 v[6:9], v124 offset:13312
	ds_read_b128 v[10:13], v124 offset:37888
	ds_read_b128 v[18:21], v124 offset:5120
	ds_read_b128 v[2:5], v124 offset:29696
	ds_read_b128 v[102:105], v125 offset:41040
	v_add_f32_e32 v122, v114, v115
	v_pk_mul_f32 v[118:119], v[98:99], v[34:35] op_sel:[1,0]
	v_add_f32_e32 v234, v116, v117
	v_add_f32_dpp v122, v122, v122 quad_perm:[1,0,3,2] row_mask:0xf bank_mask:0xf bound_ctrl:1
	v_pk_mul_f32 v[120:121], v[98:99], v[36:37] op_sel:[1,0]
	v_add_f32_dpp v226, v226, v226 row_mirror row_mask:0xf bank_mask:0xf bound_ctrl:1
	v_add_f32_dpp v122, v122, v122 quad_perm:[2,3,0,1] row_mask:0xf bank_mask:0xf bound_ctrl:1
	v_pk_fma_f32 v[166:167], v[166:167], v[26:27], v[118:119]
	v_add_f32_dpp v226, v234, v234 row_mirror row_mask:0xf bank_mask:0xc bound_ctrl:1
	v_add_f32_dpp v122, v122, v122 row_half_mirror row_mask:0xf bank_mask:0xf bound_ctrl:1
	v_pk_fma_f32 v[164:165], v[164:165], v[28:29], v[120:121]
	s_nop 0
	v_add_f32_dpp v122, v122, v122 row_mirror row_mask:0xf bank_mask:0xf bound_ctrl:1
	s_nop 0
	v_pk_fma_f32 v[166:167], v[30:31], v[122:123], v[166:167] op_sel_hi:[1,0,1]
	v_pk_fma_f32 v[164:165], v[32:33], v[122:123], v[164:165] op_sel_hi:[1,0,1]
	s_waitcnt lgkmcnt(11)
	v_pk_mul_f32 v[114:115], v[166:167], v[42:43]
	v_pk_mul_f32 v[116:117], v[166:167], v[38:39]
	v_pk_fma_f32 v[114:115], v[164:165], v[44:45], v[114:115]
	v_pk_fma_f32 v[116:117], v[164:165], v[40:41], v[116:117]
	ds_read_b128 v[34:37], v124 offset:21760
	ds_read_b128 v[26:29], v124 offset:13568
	ds_read_b128 v[30:33], v124 offset:38144
	ds_read_b128 v[38:41], v124 offset:5376
	ds_read_b128 v[22:25], v124 offset:29952
	v_add_f32_e32 v122, v114, v115
	v_pk_mul_f32 v[118:119], v[100:101], v[54:55] op_sel_hi:[0,1]
	v_add_f32_e32 v235, v116, v117
	v_add_f32_dpp v122, v122, v122 quad_perm:[1,0,3,2] row_mask:0xf bank_mask:0xf bound_ctrl:1
	v_pk_mul_f32 v[120:121], v[100:101], v[56:57] op_sel_hi:[0,1]
	v_add_f32_dpp v227, v227, v227 row_mirror row_mask:0xf bank_mask:0xf bound_ctrl:1
	v_add_f32_dpp v122, v122, v122 quad_perm:[2,3,0,1] row_mask:0xf bank_mask:0xf bound_ctrl:1
	v_pk_fma_f32 v[166:167], v[166:167], v[46:47], v[118:119]
	v_add_f32_dpp v227, v235, v235 row_mirror row_mask:0xf bank_mask:0xc bound_ctrl:1
	v_add_f32_dpp v122, v122, v122 row_half_mirror row_mask:0xf bank_mask:0xf bound_ctrl:1
	v_pk_fma_f32 v[164:165], v[164:165], v[48:49], v[120:121]
	v_add_f32_dpp v220, v220, v220 row_half_mirror row_mask:0xf bank_mask:0xf bound_ctrl:1
	v_add_f32_dpp v122, v122, v122 row_mirror row_mask:0xf bank_mask:0xf bound_ctrl:1
	v_add_f32_dpp v221, v221, v221 row_half_mirror row_mask:0xf bank_mask:0xf bound_ctrl:1
	v_add_f32_dpp v222, v222, v222 row_half_mirror row_mask:0xf bank_mask:0xf bound_ctrl:1
	v_pk_fma_f32 v[166:167], v[50:51], v[122:123], v[166:167] op_sel_hi:[1,0,1]
	v_pk_fma_f32 v[164:165], v[52:53], v[122:123], v[164:165] op_sel_hi:[1,0,1]
	v_add_f32_dpp v223, v223, v223 row_half_mirror row_mask:0xf bank_mask:0xf bound_ctrl:1
	v_add_f32_dpp v220, v224, v224 row_half_mirror row_mask:0xf bank_mask:0xa bound_ctrl:1
	s_waitcnt lgkmcnt(11)
	v_pk_mul_f32 v[114:115], v[166:167], v[62:63]
	v_pk_mul_f32 v[116:117], v[166:167], v[58:59]
	v_pk_fma_f32 v[114:115], v[164:165], v[64:65], v[114:115]
	v_pk_fma_f32 v[116:117], v[164:165], v[60:61], v[116:117]
	ds_read_b128 v[54:57], v124 offset:22016
	ds_read_b128 v[46:49], v124 offset:13824
	ds_read_b128 v[50:53], v124 offset:38400
	ds_read_b128 v[58:61], v124 offset:5632
	ds_read_b128 v[42:45], v124 offset:30208
	v_add_f32_e32 v122, v114, v115
	v_pk_mul_f32 v[118:119], v[100:101], v[74:75] op_sel:[1,0]
	v_add_f32_e32 v204, v116, v117
	v_add_f32_dpp v122, v122, v122 quad_perm:[1,0,3,2] row_mask:0xf bank_mask:0xf bound_ctrl:1
	v_pk_mul_f32 v[120:121], v[100:101], v[76:77] op_sel:[1,0]
	v_add_f32_dpp v221, v225, v225 row_half_mirror row_mask:0xf bank_mask:0xa bound_ctrl:1
	v_add_f32_dpp v122, v122, v122 quad_perm:[2,3,0,1] row_mask:0xf bank_mask:0xf bound_ctrl:1
	v_pk_fma_f32 v[166:167], v[166:167], v[66:67], v[118:119]
	v_add_f32_dpp v222, v226, v226 row_half_mirror row_mask:0xf bank_mask:0xa bound_ctrl:1
	v_add_f32_dpp v122, v122, v122 row_half_mirror row_mask:0xf bank_mask:0xf bound_ctrl:1
	v_pk_fma_f32 v[164:165], v[164:165], v[68:69], v[120:121]
	v_add_f32_dpp v223, v227, v227 row_half_mirror row_mask:0xf bank_mask:0xa bound_ctrl:1
	v_add_f32_dpp v122, v122, v122 row_mirror row_mask:0xf bank_mask:0xf bound_ctrl:1
	v_add_f32_dpp v220, v220, v220 quad_perm:[1,0,3,2] row_mask:0xf bank_mask:0xf bound_ctrl:1
	v_add_f32_dpp v221, v221, v221 quad_perm:[1,0,3,2] row_mask:0xf bank_mask:0xf bound_ctrl:1
	v_pk_fma_f32 v[166:167], v[70:71], v[122:123], v[166:167] op_sel_hi:[1,0,1]
	v_pk_fma_f32 v[164:165], v[72:73], v[122:123], v[164:165] op_sel_hi:[1,0,1]
	v_add_f32_dpp v222, v222, v222 quad_perm:[1,0,3,2] row_mask:0xf bank_mask:0xf bound_ctrl:1
	v_add_f32_dpp v223, v223, v223 quad_perm:[1,0,3,2] row_mask:0xf bank_mask:0xf bound_ctrl:1
	s_waitcnt lgkmcnt(11)
; #define LAS __attribute__((address_space(3)))
; template <int CTRL> __device__ __forceinline__ float dpp_f(float x) { return __int_as_float(__builtin_amdgcn_update_dpp(0, __float_as_int(x), CTRL, 0xf, 0xf, false)); }
; __device__ __forceinline__ void phase_scan(const Params& p, LAS unsigned char* lds) {
;     ...
;                         for (int u16 = 0; u16 < 16; ++u16) {
;                             const int s = 16 * hb + u16;
;                             const int sn = (s + 1) & 31;
;                             const f32x4 a_n = *(const LAS f32x4*)(sA + sn * 64), w_n = *(const LAS f32x4*)(sW + sn * 64), b_n = *(const LAS f32x4*)(sB + sn * 64);
;                             const f32x4 k_n = *(const LAS f32x4*)(sK + sn * 64), r_n = *(const LAS f32x4*)(sR + sn * 64);
;                             const float v = vq[u16 >> 2][u16 & 3];
;                             const f32x2 vv = {v, v};
;                             f32x2 pp = S01 * (f32x2){a_[0], a_[1]}; pp = S23 * (f32x2){a_[2], a_[3]} + pp;
;                             f32x2 yy = S01 * (f32x2){rp[0], rp[1]}; yy = S23 * (f32x2){rp[2], rp[3]} + yy;
;                             float sa = pp[0] + pp[1], y = yy[0] + yy[1];
;                             sa += dpp_f<0xB1>(sa); y += dpp_f<0xB1>(y);
;                             sa += dpp_f<0x4E>(sa); y += dpp_f<0x4E>(y);
;                             sa += dpp_f<0x141>(sa); y += dpp_f<0x141>(y);
;                             sa += dpp_f<0x140>(sa); y += dpp_f<0x140>(y);
;                             sY[((s - 1) & 31) * 16 + srow] = y;
;                             const f32x2 sv = {sa, sa};
;                             S01 = S01 * (f32x2){w_[0], w_[1]} + vv * (f32x2){k_[0], k_[1]};
;                             S23 = S23 * (f32x2){w_[2], w_[3]} + vv * (f32x2){k_[2], k_[3]};
;                             S01 = sv * (f32x2){b_[0], b_[1]} + S01;
;                             S23 = sv * (f32x2){b_[2], b_[3]} + S23;
;                             rp = r_;
;                             a_ = a_n; w_ = w_n; b_ = b_n; k_ = k_n; r_ = r_n;
	v_pk_mul_f32 v[114:115], v[166:167], v[2:3]
	v_pk_mul_f32 v[116:117], v[166:167], v[78:79]
	v_pk_fma_f32 v[114:115], v[164:165], v[4:5], v[114:115]
	v_pk_fma_f32 v[116:117], v[164:165], v[80:81], v[116:117]
	ds_read_b128 v[74:77], v124 offset:22272
	ds_read_b128 v[66:69], v124 offset:14080
	ds_read_b128 v[70:73], v124 offset:38656
	ds_read_b128 v[78:81], v124 offset:5888
	ds_read_b128 v[62:65], v124 offset:30464
	v_add_f32_e32 v122, v114, v115
	s_waitcnt lgkmcnt(15)
	v_pk_mul_f32 v[118:119], v[102:103], v[14:15] op_sel_hi:[0,1]
	v_add_f32_e32 v205, v116, v117
	v_add_f32_dpp v122, v122, v122 quad_perm:[1,0,3,2] row_mask:0xf bank_mask:0xf bound_ctrl:1
	v_pk_mul_f32 v[120:121], v[102:103], v[16:17] op_sel_hi:[0,1]
	v_add_f32_dpp v220, v220, v220 quad_perm:[2,3,0,1] row_mask:0xf bank_mask:0xf bound_ctrl:1
	v_add_f32_dpp v122, v122, v122 quad_perm:[2,3,0,1] row_mask:0xf bank_mask:0xf bound_ctrl:1
	v_pk_fma_f32 v[166:167], v[166:167], v[6:7], v[118:119]
	v_add_f32_dpp v221, v221, v221 quad_perm:[2,3,0,1] row_mask:0xf bank_mask:0xf bound_ctrl:1
	v_add_f32_dpp v122, v122, v122 row_half_mirror row_mask:0xf bank_mask:0xf bound_ctrl:1
	v_pk_fma_f32 v[164:165], v[164:165], v[8:9], v[120:121]
	v_add_f32_dpp v222, v222, v222 quad_perm:[2,3,0,1] row_mask:0xf bank_mask:0xf bound_ctrl:1
	v_add_f32_dpp v122, v122, v122 row_mirror row_mask:0xf bank_mask:0xf bound_ctrl:1
	v_add_f32_dpp v223, v223, v223 quad_perm:[2,3,0,1] row_mask:0xf bank_mask:0xf bound_ctrl:1
	v_cndmask_b32_e64 v202, v220, v221, s[34:35]
	v_pk_fma_f32 v[166:167], v[10:11], v[122:123], v[166:167] op_sel_hi:[1,0,1]
	v_pk_fma_f32 v[164:165], v[12:13], v[122:123], v[164:165] op_sel_hi:[1,0,1]
	v_cndmask_b32_e64 v202, v202, v222, s[56:57]
	v_cndmask_b32_e64 v202, v202, v223, s[98:99]
	s_waitcnt lgkmcnt(10)
	v_pk_mul_f32 v[114:115], v[166:167], v[22:23]
	v_pk_mul_f32 v[116:117], v[166:167], v[18:19]
	v_pk_fma_f32 v[114:115], v[164:165], v[24:25], v[114:115]
	v_pk_fma_f32 v[116:117], v[164:165], v[20:21], v[116:117]
	ds_read_b128 v[14:17], v124 offset:22528
	ds_read_b128 v[6:9], v124 offset:14336
	ds_read_b128 v[10:13], v124 offset:38912
	ds_read_b128 v[18:21], v124 offset:6144
	ds_read_b128 v[2:5], v124 offset:30720
	ds_read_b128 v[106:109], v125 offset:41056
	v_add_f32_e32 v122, v114, v115
	v_pk_mul_f32 v[118:119], v[102:103], v[34:35] op_sel:[1,0]
	v_add_f32_e32 v206, v116, v117
	v_add_f32_dpp v122, v122, v122 quad_perm:[1,0,3,2] row_mask:0xf bank_mask:0xf bound_ctrl:1
	v_pk_mul_f32 v[120:121], v[102:103], v[36:37] op_sel:[1,0]
	v_cvt_f16_f32_e32 v203, v202
	v_add_f32_dpp v122, v122, v122 quad_perm:[2,3,0,1] row_mask:0xf bank_mask:0xf bound_ctrl:1
	v_pk_fma_f32 v[166:167], v[166:167], v[26:27], v[118:119]
	global_store_short v[126:127], v203, off
	v_add_f32_dpp v122, v122, v122 row_half_mirror row_mask:0xf bank_mask:0xf bound_ctrl:1
	v_pk_fma_f32 v[164:165], v[164:165], v[28:29], v[120:121]
	v_lshl_add_u64 v[126:127], v[126:127], 0, s[100:101]
	v_add_f32_dpp v122, v122, v122 row_mirror row_mask:0xf bank_mask:0xf bound_ctrl:1
	s_nop 0
	v_pk_fma_f32 v[166:167], v[30:31], v[122:123], v[166:167] op_sel_hi:[1,0,1]
	v_pk_fma_f32 v[164:165], v[32:33], v[122:123], v[164:165] op_sel_hi:[1,0,1]
	s_waitcnt lgkmcnt(11)
	v_pk_mul_f32 v[114:115], v[166:167], v[42:43]
	v_pk_mul_f32 v[116:117], v[166:167], v[38:39]
	v_pk_fma_f32 v[114:115], v[164:165], v[44:45], v[114:115]
	v_pk_fma_f32 v[116:117], v[164:165], v[40:41], v[116:117]
	ds_read_b128 v[34:37], v124 offset:22784
	ds_read_b128 v[26:29], v124 offset:14592
	ds_read_b128 v[30:33], v124 offset:39168
	ds_read_b128 v[38:41], v124 offset:6400
	ds_read_b128 v[22:25], v124 offset:30976
	v_add_f32_e32 v122, v114, v115
	v_pk_mul_f32 v[118:119], v[104:105], v[54:55] op_sel_hi:[0,1]
	v_add_f32_e32 v207, v116, v117
	v_add_f32_dpp v122, v122, v122 quad_perm:[1,0,3,2] row_mask:0xf bank_mask:0xf bound_ctrl:1
	v_pk_mul_f32 v[120:121], v[104:105], v[56:57] op_sel_hi:[0,1]
	s_nop 0
	v_add_f32_dpp v122, v122, v122 quad_perm:[2,3,0,1] row_mask:0xf bank_mask:0xf bound_ctrl:1
	v_pk_fma_f32 v[166:167], v[166:167], v[46:47], v[118:119]
	s_nop 0
	v_add_f32_dpp v122, v122, v122 row_half_mirror row_mask:0xf bank_mask:0xf bound_ctrl:1
	v_pk_fma_f32 v[164:165], v[164:165], v[48:49], v[120:121]
	s_nop 0
	v_add_f32_dpp v122, v122, v122 row_mirror row_mask:0xf bank_mask:0xf bound_ctrl:1
	s_nop 0
	v_pk_fma_f32 v[166:167], v[50:51], v[122:123], v[166:167] op_sel_hi:[1,0,1]
	v_pk_fma_f32 v[164:165], v[52:53], v[122:123], v[164:165] op_sel_hi:[1,0,1]
	s_waitcnt lgkmcnt(11)
	v_pk_mul_f32 v[114:115], v[166:167], v[62:63]
	v_pk_mul_f32 v[116:117], v[166:167], v[58:59]
	v_pk_fma_f32 v[114:115], v[164:165], v[64:65], v[114:115]
	v_pk_fma_f32 v[116:117], v[164:165], v[60:61], v[116:117]
	ds_read_b128 v[54:57], v124 offset:23040
	ds_read_b128 v[46:49], v124 offset:14848
	ds_read_b128 v[50:53], v124 offset:39424
	ds_read_b128 v[58:61], v124 offset:6656
	ds_read_b128 v[42:45], v124 offset:31232
	v_add_f32_e32 v122, v114, v115
	v_pk_mul_f32 v[118:119], v[104:105], v[74:75] op_sel:[1,0]
	v_add_f32_e32 v208, v116, v117
	v_add_f32_dpp v122, v122, v122 quad_perm:[1,0,3,2] row_mask:0xf bank_mask:0xf bound_ctrl:1
	v_pk_mul_f32 v[120:121], v[104:105], v[76:77] op_sel:[1,0]
	s_nop 0
	v_add_f32_dpp v122, v122, v122 quad_perm:[2,3,0,1] row_mask:0xf bank_mask:0xf bound_ctrl:1
	v_pk_fma_f32 v[166:167], v[166:167], v[66:67], v[118:119]
	s_nop 0
	v_add_f32_dpp v122, v122, v122 row_half_mirror row_mask:0xf bank_mask:0xf bound_ctrl:1
	v_pk_fma_f32 v[164:165], v[164:165], v[68:69], v[120:121]
	s_nop 0
	v_add_f32_dpp v122, v122, v122 row_mirror row_mask:0xf bank_mask:0xf bound_ctrl:1
	s_nop 0
	v_pk_fma_f32 v[166:167], v[70:71], v[122:123], v[166:167] op_sel_hi:[1,0,1]
	v_pk_fma_f32 v[164:165], v[72:73], v[122:123], v[164:165] op_sel_hi:[1,0,1]
	s_waitcnt lgkmcnt(11)
; #define LAS __attribute__((address_space(3)))
; __device__ __forceinline__ void phase_scan(const Params& p, LAS unsigned char* lds) {
;     ...
;                         for (int u16 = 0; u16 < 16; ++u16) {
;                             const int s = 16 * hb + u16;
;                             const int sn = (s + 1) & 31;
;                             const f32x4 a_n = *(const LAS f32x4*)(sA + sn * 64), w_n = *(const LAS f32x4*)(sW + sn * 64), b_n = *(const LAS f32x4*)(sB + sn * 64);
;                             const f32x4 k_n = *(const LAS f32x4*)(sK + sn * 64), r_n = *(const LAS f32x4*)(sR + sn * 64);
;                             const float v = vq[u16 >> 2][u16 & 3];
;                             const f32x2 vv = {v, v};
;                             f32x2 pp = S01 * (f32x2){a_[0], a_[1]}; pp = S23 * (f32x2){a_[2], a_[3]} + pp;
;                             f32x2 yy = S01 * (f32x2){rp[0], rp[1]}; yy = S23 * (f32x2){rp[2], rp[3]} + yy;
;                             float sa = pp[0] + pp[1], y = yy[0] + yy[1];
;                             sa += dpp_f<0xB1>(sa); y += dpp_f<0xB1>(y);
;                             sa += dpp_f<0x4E>(sa); y += dpp_f<0x4E>(y);
;                             sa += dpp_f<0x141>(sa); y += dpp_f<0x141>(y);
;                             sa += dpp_f<0x140>(sa); y += dpp_f<0x140>(y);
;                             sY[((s - 1) & 31) * 16 + srow] = y;
;                             const f32x2 sv = {sa, sa};
;                             S01 = S01 * (f32x2){w_[0], w_[1]} + vv * (f32x2){k_[0], k_[1]};
;                             S23 = S23 * (f32x2){w_[2], w_[3]} + vv * (f32x2){k_[2], k_[3]};
;                             S01 = sv * (f32x2){b_[0], b_[1]} + S01;
;                             S23 = sv * (f32x2){b_[2], b_[3]} + S23;
;                             rp = r_;
;                             a_ = a_n; w_ = w_n; b_ = b_n; k_ = k_n; r_ = r_n;
;                         }
; #pragma unroll
;                         for (int u = 0; u < 4; ++u) vq[u] = vn[u];
;                     }
;                     { f32x2 yy = S01 * (f32x2){rp[0], rp[1]}; yy = S23 * (f32x2){rp[2], rp[3]} + yy; sY[31 * 16 + srow] = red16(yy[0] + yy[1]); }
;                     __builtin_amdgcn_s_setprio(0);
	v_pk_mul_f32 v[114:115], v[166:167], v[2:3]
	v_pk_mul_f32 v[116:117], v[166:167], v[78:79]
	v_pk_fma_f32 v[114:115], v[164:165], v[4:5], v[114:115]
	v_pk_fma_f32 v[116:117], v[164:165], v[80:81], v[116:117]
	ds_read_b128 v[74:77], v124 offset:23296
	ds_read_b128 v[66:69], v124 offset:15104
	ds_read_b128 v[70:73], v124 offset:39680
	ds_read_b128 v[78:81], v124 offset:6912
	ds_read_b128 v[62:65], v124 offset:31488
	v_add_f32_e32 v122, v114, v115
	s_waitcnt lgkmcnt(15)
	v_pk_mul_f32 v[118:119], v[106:107], v[14:15] op_sel_hi:[0,1]
	v_add_f32_e32 v209, v116, v117
	v_add_f32_dpp v122, v122, v122 quad_perm:[1,0,3,2] row_mask:0xf bank_mask:0xf bound_ctrl:1
	v_pk_mul_f32 v[120:121], v[106:107], v[16:17] op_sel_hi:[0,1]
	s_nop 0
	v_add_f32_dpp v122, v122, v122 quad_perm:[2,3,0,1] row_mask:0xf bank_mask:0xf bound_ctrl:1
	v_pk_fma_f32 v[166:167], v[166:167], v[6:7], v[118:119]
	s_nop 0
	v_add_f32_dpp v122, v122, v122 row_half_mirror row_mask:0xf bank_mask:0xf bound_ctrl:1
	v_pk_fma_f32 v[164:165], v[164:165], v[8:9], v[120:121]
	s_nop 0
	v_add_f32_dpp v122, v122, v122 row_mirror row_mask:0xf bank_mask:0xf bound_ctrl:1
	s_nop 0
	v_pk_fma_f32 v[166:167], v[10:11], v[122:123], v[166:167] op_sel_hi:[1,0,1]
	v_pk_fma_f32 v[164:165], v[12:13], v[122:123], v[164:165] op_sel_hi:[1,0,1]
	s_waitcnt lgkmcnt(10)
	v_pk_mul_f32 v[114:115], v[166:167], v[22:23]
	v_pk_mul_f32 v[116:117], v[166:167], v[18:19]
	v_pk_fma_f32 v[114:115], v[164:165], v[24:25], v[114:115]
	v_pk_fma_f32 v[116:117], v[164:165], v[20:21], v[116:117]
	ds_read_b128 v[14:17], v124 offset:23552
	ds_read_b128 v[6:9], v124 offset:15360
	ds_read_b128 v[10:13], v124 offset:39936
	ds_read_b128 v[18:21], v124 offset:7168
	ds_read_b128 v[2:5], v124 offset:31744
	ds_read_b128 v[110:113], v125 offset:41072
	v_add_f32_e32 v122, v114, v115
	v_pk_mul_f32 v[118:119], v[106:107], v[34:35] op_sel:[1,0]
	v_add_f32_e32 v210, v116, v117
	v_add_f32_dpp v122, v122, v122 quad_perm:[1,0,3,2] row_mask:0xf bank_mask:0xf bound_ctrl:1
	v_pk_mul_f32 v[120:121], v[106:107], v[36:37] op_sel:[1,0]
	s_nop 0
	v_add_f32_dpp v122, v122, v122 quad_perm:[2,3,0,1] row_mask:0xf bank_mask:0xf bound_ctrl:1
	v_pk_fma_f32 v[166:167], v[166:167], v[26:27], v[118:119]
	s_nop 0
	v_add_f32_dpp v122, v122, v122 row_half_mirror row_mask:0xf bank_mask:0xf bound_ctrl:1
	v_pk_fma_f32 v[164:165], v[164:165], v[28:29], v[120:121]
	s_nop 0
	v_add_f32_dpp v122, v122, v122 row_mirror row_mask:0xf bank_mask:0xf bound_ctrl:1
	s_nop 0
	v_pk_fma_f32 v[166:167], v[30:31], v[122:123], v[166:167] op_sel_hi:[1,0,1]
	v_pk_fma_f32 v[164:165], v[32:33], v[122:123], v[164:165] op_sel_hi:[1,0,1]
	s_waitcnt lgkmcnt(11)
	v_pk_mul_f32 v[114:115], v[166:167], v[42:43]
	v_pk_mul_f32 v[116:117], v[166:167], v[38:39]
	v_pk_fma_f32 v[114:115], v[164:165], v[44:45], v[114:115]
	v_pk_fma_f32 v[116:117], v[164:165], v[40:41], v[116:117]
	ds_read_b128 v[34:37], v124 offset:23808
	ds_read_b128 v[26:29], v124 offset:15616
	ds_read_b128 v[30:33], v124 offset:40192
	ds_read_b128 v[38:41], v124 offset:7424
	ds_read_b128 v[22:25], v124 offset:32000
	v_add_f32_e32 v122, v114, v115
	v_pk_mul_f32 v[118:119], v[108:109], v[54:55] op_sel_hi:[0,1]
	v_add_f32_e32 v211, v116, v117
	v_add_f32_dpp v122, v122, v122 quad_perm:[1,0,3,2] row_mask:0xf bank_mask:0xf bound_ctrl:1
	v_pk_mul_f32 v[120:121], v[108:109], v[56:57] op_sel_hi:[0,1]
	s_nop 0
	v_add_f32_dpp v122, v122, v122 quad_perm:[2,3,0,1] row_mask:0xf bank_mask:0xf bound_ctrl:1
	v_pk_fma_f32 v[166:167], v[166:167], v[46:47], v[118:119]
	s_nop 0
	v_add_f32_dpp v122, v122, v122 row_half_mirror row_mask:0xf bank_mask:0xf bound_ctrl:1
	v_pk_fma_f32 v[164:165], v[164:165], v[48:49], v[120:121]
	s_nop 0
	v_add_f32_dpp v122, v122, v122 row_mirror row_mask:0xf bank_mask:0xf bound_ctrl:1
	s_nop 0
	v_pk_fma_f32 v[166:167], v[50:51], v[122:123], v[166:167] op_sel_hi:[1,0,1]
	v_pk_fma_f32 v[164:165], v[52:53], v[122:123], v[164:165] op_sel_hi:[1,0,1]
	s_waitcnt lgkmcnt(11)
	v_pk_mul_f32 v[114:115], v[166:167], v[62:63]
	v_pk_mul_f32 v[116:117], v[166:167], v[58:59]
	v_pk_fma_f32 v[114:115], v[164:165], v[64:65], v[114:115]
	v_pk_fma_f32 v[116:117], v[164:165], v[60:61], v[116:117]
	ds_read_b128 v[54:57], v124 offset:24064
	ds_read_b128 v[46:49], v124 offset:15872
	ds_read_b128 v[50:53], v124 offset:40448
	ds_read_b128 v[58:61], v124 offset:7680
	ds_read_b128 v[42:45], v124 offset:32256
	v_add_f32_e32 v122, v114, v115
	v_pk_mul_f32 v[118:119], v[108:109], v[74:75] op_sel:[1,0]
	v_add_f32_e32 v212, v116, v117
	v_add_f32_dpp v122, v122, v122 quad_perm:[1,0,3,2] row_mask:0xf bank_mask:0xf bound_ctrl:1
	v_pk_mul_f32 v[120:121], v[108:109], v[76:77] op_sel:[1,0]
	s_nop 0
	v_add_f32_dpp v122, v122, v122 quad_perm:[2,3,0,1] row_mask:0xf bank_mask:0xf bound_ctrl:1
	v_pk_fma_f32 v[166:167], v[166:167], v[66:67], v[118:119]
	s_nop 0
	v_add_f32_dpp v122, v122, v122 row_half_mirror row_mask:0xf bank_mask:0xf bound_ctrl:1
	v_pk_fma_f32 v[164:165], v[164:165], v[68:69], v[120:121]
	s_nop 0
	v_add_f32_dpp v122, v122, v122 row_mirror row_mask:0xf bank_mask:0xf bound_ctrl:1
	s_nop 0
	v_pk_fma_f32 v[166:167], v[70:71], v[122:123], v[166:167] op_sel_hi:[1,0,1]
	v_pk_fma_f32 v[164:165], v[72:73], v[122:123], v[164:165] op_sel_hi:[1,0,1]
	s_waitcnt lgkmcnt(11)
	v_pk_mul_f32 v[114:115], v[166:167], v[2:3]
	v_pk_mul_f32 v[116:117], v[166:167], v[78:79]
	v_pk_fma_f32 v[114:115], v[164:165], v[4:5], v[114:115]
	v_pk_fma_f32 v[116:117], v[164:165], v[80:81], v[116:117]
	ds_read_b128 v[74:77], v124 offset:24320
	ds_read_b128 v[66:69], v124 offset:16128
	ds_read_b128 v[70:73], v124 offset:40704
	ds_read_b128 v[78:81], v124 offset:7936
	ds_read_b128 v[62:65], v124 offset:32512
	v_add_f32_e32 v122, v114, v115
	s_waitcnt lgkmcnt(15)
	v_pk_mul_f32 v[118:119], v[110:111], v[14:15] op_sel_hi:[0,1]
	v_add_f32_e32 v213, v116, v117
	v_add_f32_dpp v122, v122, v122 quad_perm:[1,0,3,2] row_mask:0xf bank_mask:0xf bound_ctrl:1
	v_pk_mul_f32 v[120:121], v[110:111], v[16:17] op_sel_hi:[0,1]
	s_nop 0
	v_add_f32_dpp v122, v122, v122 quad_perm:[2,3,0,1] row_mask:0xf bank_mask:0xf bound_ctrl:1
	v_pk_fma_f32 v[166:167], v[166:167], v[6:7], v[118:119]
	s_nop 0
	v_add_f32_dpp v122, v122, v122 row_half_mirror row_mask:0xf bank_mask:0xf bound_ctrl:1
	v_pk_fma_f32 v[164:165], v[164:165], v[8:9], v[120:121]
	s_nop 0
	v_add_f32_dpp v122, v122, v122 row_mirror row_mask:0xf bank_mask:0xf bound_ctrl:1
	s_nop 0
	v_pk_fma_f32 v[166:167], v[10:11], v[122:123], v[166:167] op_sel_hi:[1,0,1]
	v_pk_fma_f32 v[164:165], v[12:13], v[122:123], v[164:165] op_sel_hi:[1,0,1]
	s_setprio 0
	s_branch .LBB0_603
; #define LAS __attribute__((address_space(3)))
; __device__ __forceinline__ void phase_scan(const Params& p, LAS unsigned char* lds) {
;     ...
;                         for (int u16 = 0; u16 < 16; ++u16) {
;                             const int s = 16 * hb + u16;
;                             const int sn = (s + 1) & 31;
;                             const f32x4 a_n = *(const LAS f32x4*)(sA + sn * 64), w_n = *(const LAS f32x4*)(sW + sn * 64), b_n = *(const LAS f32x4*)(sB + sn * 64);
;                             const f32x4 k_n = *(const LAS f32x4*)(sK + sn * 64), r_n = *(const LAS f32x4*)(sR + sn * 64);
;                             const float v = vq[u16 >> 2][u16 & 3];
;                             const f32x2 vv = {v, v};
;                             f32x2 pp = S01 * (f32x2){a_[0], a_[1]}; pp = S23 * (f32x2){a_[2], a_[3]} + pp;
;                             f32x2 yy = S01 * (f32x2){rp[0], rp[1]}; yy = S23 * (f32x2){rp[2], rp[3]} + yy;
;                             float sa = pp[0] + pp[1], y = yy[0] + yy[1];
;                             sa += dpp_f<0xB1>(sa); y += dpp_f<0xB1>(y);
;                             sa += dpp_f<0x4E>(sa); y += dpp_f<0x4E>(y);
;                             sa += dpp_f<0x141>(sa); y += dpp_f<0x141>(y);
;                             sa += dpp_f<0x140>(sa); y += dpp_f<0x140>(y);
;                             sY[((s - 1) & 31) * 16 + srow] = y;
;                             const f32x2 sv = {sa, sa};
;                             S01 = S01 * (f32x2){w_[0], w_[1]} + vv * (f32x2){k_[0], k_[1]};
;                             S23 = S23 * (f32x2){w_[2], w_[3]} + vv * (f32x2){k_[2], k_[3]};
;                             S01 = sv * (f32x2){b_[0], b_[1]} + S01;
;                             S23 = sv * (f32x2){b_[2], b_[3]} + S23;
;                             rp = r_;
;                             a_ = a_n; w_ = w_n; b_ = b_n; k_ = k_n; r_ = r_n;
;                         }
; #pragma unroll
;                         for (int u = 0; u < 4; ++u) vq[u] = vn[u];
;                     }
;                     { f32x2 yy = S01 * (f32x2){rp[0], rp[1]}; yy = S23 * (f32x2){rp[2], rp[3]} + yy; sY[31 * 16 + srow] = red16(yy[0] + yy[1]); }
;                     __builtin_amdgcn_s_setprio(0);
.LBB0_620:
	s_mov_b64 s[10:11], 0
	s_cmp_eq_u64 s[0:1], 0
	s_cbranch_scc0 .LBB0_594
	s_setprio 3
	s_mov_b32 s14, 0x3fff3fff
	s_mov_b32 s15, s14
	v_pk_mul_f32 v[114:115], v[166:167], v[22:23]
	v_pk_mul_f32 v[116:117], v[166:167], v[18:19]
	v_pk_fma_f32 v[114:115], v[164:165], v[24:25], v[114:115]
	v_pk_fma_f32 v[116:117], v[164:165], v[20:21], v[116:117]
	v_add_f32_e32 v122, v114, v115
	v_pk_mul_f32 v[118:119], v[110:111], v[34:35] op_sel:[1,0]
	v_add_f32_e32 v214, v116, v117
	v_add_f32_dpp v122, v122, v122 quad_perm:[1,0,3,2] row_mask:0xf bank_mask:0xf bound_ctrl:1
	v_pk_mul_f32 v[120:121], v[110:111], v[36:37] op_sel:[1,0]
	v_add_f32_dpp v204, v204, v204 row_mirror row_mask:0xf bank_mask:0xf bound_ctrl:1
	v_add_f32_dpp v122, v122, v122 quad_perm:[2,3,0,1] row_mask:0xf bank_mask:0xf bound_ctrl:1
	v_pk_fma_f32 v[166:167], v[166:167], v[26:27], v[118:119]
	v_add_f32_dpp v204, v212, v212 row_mirror row_mask:0xf bank_mask:0xc bound_ctrl:1
	v_add_f32_dpp v122, v122, v122 row_half_mirror row_mask:0xf bank_mask:0xf bound_ctrl:1
	v_pk_fma_f32 v[164:165], v[164:165], v[28:29], v[120:121]
	v_add_f32_dpp v205, v205, v205 row_mirror row_mask:0xf bank_mask:0xf bound_ctrl:1
	v_add_f32_dpp v122, v122, v122 row_mirror row_mask:0xf bank_mask:0xf bound_ctrl:1
	v_add_f32_dpp v205, v213, v213 row_mirror row_mask:0xf bank_mask:0xc bound_ctrl:1
	v_add_f32_dpp v206, v206, v206 row_mirror row_mask:0xf bank_mask:0xf bound_ctrl:1
	v_pk_fma_f32 v[166:167], v[30:31], v[122:123], v[166:167] op_sel_hi:[1,0,1]
	v_pk_fma_f32 v[164:165], v[32:33], v[122:123], v[164:165] op_sel_hi:[1,0,1]
	v_add_f32_dpp v206, v214, v214 row_mirror row_mask:0xf bank_mask:0xc bound_ctrl:1
	v_pk_mul_f32 v[114:115], v[166:167], v[42:43]
	v_pk_mul_f32 v[116:117], v[166:167], v[38:39]
	v_pk_fma_f32 v[114:115], v[164:165], v[44:45], v[114:115]
	v_pk_fma_f32 v[116:117], v[164:165], v[40:41], v[116:117]
	v_add_f32_e32 v122, v114, v115
	v_pk_mul_f32 v[118:119], v[112:113], v[54:55] op_sel_hi:[0,1]
	v_add_f32_e32 v215, v116, v117
	v_add_f32_dpp v122, v122, v122 quad_perm:[1,0,3,2] row_mask:0xf bank_mask:0xf bound_ctrl:1
	v_pk_mul_f32 v[120:121], v[112:113], v[56:57] op_sel_hi:[0,1]
	v_add_f32_dpp v207, v207, v207 row_mirror row_mask:0xf bank_mask:0xf bound_ctrl:1
	v_add_f32_dpp v122, v122, v122 quad_perm:[2,3,0,1] row_mask:0xf bank_mask:0xf bound_ctrl:1
	v_pk_fma_f32 v[166:167], v[166:167], v[46:47], v[118:119]
	v_add_f32_dpp v207, v215, v215 row_mirror row_mask:0xf bank_mask:0xc bound_ctrl:1
	v_add_f32_dpp v122, v122, v122 row_half_mirror row_mask:0xf bank_mask:0xf bound_ctrl:1
	v_pk_fma_f32 v[164:165], v[164:165], v[48:49], v[120:121]
	s_nop 0
	v_add_f32_dpp v122, v122, v122 row_mirror row_mask:0xf bank_mask:0xf bound_ctrl:1
	s_nop 0
	v_pk_fma_f32 v[166:167], v[50:51], v[122:123], v[166:167] op_sel_hi:[1,0,1]
	v_pk_fma_f32 v[164:165], v[52:53], v[122:123], v[164:165] op_sel_hi:[1,0,1]
	v_pk_mul_f32 v[114:115], v[166:167], v[62:63]
	v_pk_mul_f32 v[116:117], v[166:167], v[58:59]
	v_pk_fma_f32 v[114:115], v[164:165], v[64:65], v[114:115]
	v_pk_fma_f32 v[116:117], v[164:165], v[60:61], v[116:117]
	v_add_f32_e32 v122, v114, v115
	v_pk_mul_f32 v[118:119], v[112:113], v[74:75] op_sel:[1,0]
	v_add_f32_e32 v216, v116, v117
	v_add_f32_dpp v122, v122, v122 quad_perm:[1,0,3,2] row_mask:0xf bank_mask:0xf bound_ctrl:1
	v_pk_mul_f32 v[120:121], v[112:113], v[76:77] op_sel:[1,0]
	v_add_f32_dpp v208, v208, v208 row_mirror row_mask:0xf bank_mask:0xf bound_ctrl:1
	v_add_f32_dpp v122, v122, v122 quad_perm:[2,3,0,1] row_mask:0xf bank_mask:0xf bound_ctrl:1
	v_pk_fma_f32 v[166:167], v[166:167], v[66:67], v[118:119]
	v_add_f32_dpp v208, v216, v216 row_mirror row_mask:0xf bank_mask:0xc bound_ctrl:1
	v_add_f32_dpp v122, v122, v122 row_half_mirror row_mask:0xf bank_mask:0xf bound_ctrl:1
	v_pk_fma_f32 v[164:165], v[164:165], v[68:69], v[120:121]
	s_nop 0
	v_add_f32_dpp v122, v122, v122 row_mirror row_mask:0xf bank_mask:0xf bound_ctrl:1
	s_nop 0
	v_pk_fma_f32 v[166:167], v[70:71], v[122:123], v[166:167] op_sel_hi:[1,0,1]
	v_pk_fma_f32 v[164:165], v[72:73], v[122:123], v[164:165] op_sel_hi:[1,0,1]
	v_pk_mul_f32 v[116:117], v[166:167], v[78:79]
	s_nop 0
	v_pk_fma_f32 v[116:117], v[164:165], v[80:81], v[116:117]
	s_nop 0
	v_add_f32_e32 v217, v116, v117
	v_mov_b32_e32 v218, 0
	v_mov_b32_e32 v219, 0
	s_nop 1
	v_add_f32_dpp v209, v209, v209 row_mirror row_mask:0xf bank_mask:0xf bound_ctrl:1
	v_add_f32_dpp v209, v217, v217 row_mirror row_mask:0xf bank_mask:0xc bound_ctrl:1
	v_add_f32_dpp v210, v210, v210 row_mirror row_mask:0xf bank_mask:0xf bound_ctrl:1
	v_add_f32_dpp v210, v218, v218 row_mirror row_mask:0xf bank_mask:0xc bound_ctrl:1
	v_add_f32_dpp v211, v211, v211 row_mirror row_mask:0xf bank_mask:0xf bound_ctrl:1
	v_add_f32_dpp v211, v219, v219 row_mirror row_mask:0xf bank_mask:0xc bound_ctrl:1
	s_nop 1
	v_add_f32_dpp v204, v204, v204 row_half_mirror row_mask:0xf bank_mask:0xf bound_ctrl:1
	v_add_f32_dpp v205, v205, v205 row_half_mirror row_mask:0xf bank_mask:0xf bound_ctrl:1
	v_add_f32_dpp v206, v206, v206 row_half_mirror row_mask:0xf bank_mask:0xf bound_ctrl:1
	v_add_f32_dpp v207, v207, v207 row_half_mirror row_mask:0xf bank_mask:0xf bound_ctrl:1
	v_add_f32_dpp v204, v208, v208 row_half_mirror row_mask:0xf bank_mask:0xa bound_ctrl:1
	v_add_f32_dpp v205, v209, v209 row_half_mirror row_mask:0xf bank_mask:0xa bound_ctrl:1
	v_add_f32_dpp v206, v210, v210 row_half_mirror row_mask:0xf bank_mask:0xa bound_ctrl:1
	v_add_f32_dpp v207, v211, v211 row_half_mirror row_mask:0xf bank_mask:0xa bound_ctrl:1
	v_add_f32_dpp v204, v204, v204 quad_perm:[1,0,3,2] row_mask:0xf bank_mask:0xf bound_ctrl:1
	v_add_f32_dpp v205, v205, v205 quad_perm:[1,0,3,2] row_mask:0xf bank_mask:0xf bound_ctrl:1
	v_add_f32_dpp v206, v206, v206 quad_perm:[1,0,3,2] row_mask:0xf bank_mask:0xf bound_ctrl:1
	v_add_f32_dpp v207, v207, v207 quad_perm:[1,0,3,2] row_mask:0xf bank_mask:0xf bound_ctrl:1
	v_add_f32_dpp v204, v204, v204 quad_perm:[2,3,0,1] row_mask:0xf bank_mask:0xf bound_ctrl:1
	v_add_f32_dpp v205, v205, v205 quad_perm:[2,3,0,1] row_mask:0xf bank_mask:0xf bound_ctrl:1
	v_add_f32_dpp v206, v206, v206 quad_perm:[2,3,0,1] row_mask:0xf bank_mask:0xf bound_ctrl:1
	v_add_f32_dpp v207, v207, v207 quad_perm:[2,3,0,1] row_mask:0xf bank_mask:0xf bound_ctrl:1
	v_cndmask_b32_e64 v202, v204, v205, s[34:35]
	v_cndmask_b32_e64 v202, v202, v206, s[56:57]
	v_cndmask_b32_e64 v202, v202, v207, s[98:99]
	v_cvt_f16_f32_e32 v203, v202
	s_mov_b64 exec, s[14:15]
	global_store_short v[128:129], v203, off
	s_mov_b64 exec, -1
	v_lshl_add_u64 v[128:129], v[128:129], 0, s[100:101]
	s_setprio 0
	s_branch .LBB0_594
